# removed redundant s_setprio 0/1 pairs in the middle of each 32-MFMA block of the GEMM loops
# baseline (speedup 1.0000x reference)
; #define PG8_STAGE(bufoff, gbase, voff) do { _Pragma("unroll") for (int _i = 0; _i < 2; ++_i) \
;         __builtin_amdgcn_global_load_lds((const unsigned*)((const char*)(gbase) + (voff)[_i]), (PG8_LAS unsigned*)(lds + (bufoff) + ldsw + _i * 8192), 16, 0, 0); } while (0)
; #define PG8_LDA(dst, b, h) do { _Pragma("unroll") for (int m = 0; m < 4; ++m) _Pragma("unroll") for (int k = 0; k < 2; ++k) dst[m][k] = *(const PG8_LAS bf16x8*)(lds + PG8_SA(b, h) + aoff + m * 2048 + k * 1024); } while (0)
; #define PG8_LDB(dst, b, h) do { _Pragma("unroll") for (int n = 0; n < 2; ++n) _Pragma("unroll") for (int k = 0; k < 2; ++k) dst[n][k] = *(const PG8_LAS bf16x8*)(lds + PG8_SB(b, h) + boff + n * 2048 + k * 1024); } while (0)
; #define PG8_MMA(ai, bj, At, Bt) do { __builtin_amdgcn_s_setprio(1); _Pragma("unroll") for (int m = 0; m < 4; ++m) _Pragma("unroll") for (int n = 0; n < 2; ++n) _Pragma("unroll") for (int k = 0; k < 2; ++k) \
;         acc[ai][bj][m][n] = __builtin_amdgcn_mfma_f32_16x16x32_bf16(Bt[n][k], At[m][k], acc[ai][bj][m][n], 0, 0, 0); __builtin_amdgcn_s_setprio(0); } while (0)
; #define PG8_WAIT_V(n) asm volatile("s_waitcnt vmcnt(" #n ")" ::: "memory")
; #define PG8_WAIT_L(n) asm volatile("s_waitcnt lgkmcnt(" #n ")" ::: "memory")
; #define PG8_BAR __builtin_amdgcn_s_barrier()
; #define PG8_SCHED __builtin_amdgcn_sched_barrier(0)
; template <class Epi, class Sched, bool ALIGN_EPI = false, bool SP2 = false>
; __device__ __forceinline__ void gemm_phase(PG8_LAS unsigned char* lds, const Gemm g, const Sched& S, const Epi& E) {
;     ...
;             PG8_LDB(B0, 0, 0); PG8_LDB(B1, 0, 1); PG8_SCHED; PG8_LDA(At, 0, 0); PG8_STAGE(PG8_SA(1, 1), a1 + hstep, voffA);
;             PG8_WAIT_V(8); PG8_WAIT_L(0); PG8_BAR; PG8_MMA(0, 0, At, B0); PG8_MMA(0, 1, At, B1); PG8_BAR; PG8_SCHED;
;             PG8_LDA(At, 0, 1); PG8_STAGE(PG8_SB(0, 0), b2, voffB); PG8_STAGE(PG8_SB(0, 1), b2 + hstep, voffB); PG8_STAGE(PG8_SA(0, 0), a2, voffA);
.LBB0_161:
	s_add_u32 s26, s8, 0xfffc0080
	s_addc_u32 s27, s9, -1
	s_add_i32 s48, 0, 0x10000
	s_cmp_eq_u32 s47, 12
	s_cselect_b32 s29, s21, s27
	s_cselect_b32 s28, s43, s26
	v_add_u32_e32 v140, s48, v148
	s_cselect_b32 s27, s19, s46
	s_cselect_b32 s26, s44, s45
	s_add_i32 s50, 0, 0x14000
	ds_read_b128 v[142:145], v140
	ds_read_b128 v[154:157], v140 offset:1024
	ds_read_b128 v[158:161], v140 offset:2048
	ds_read_b128 v[162:165], v140 offset:3072
	v_add_u32_e32 v140, s50, v148
	ds_read_b128 v[166:169], v140
	ds_read_b128 v[170:173], v140 offset:1024
	ds_read_b128 v[174:177], v140 offset:2048
	ds_read_b128 v[178:181], v140 offset:3072
	v_lshl_add_u64 v[146:147], s[8:9], 0, v[136:137]
	s_add_i32 m0, s31, 0xc000
	ds_read_b128 v[182:185], v153
	ds_read_b128 v[186:189], v153 offset:1024
	ds_read_b128 v[202:205], v153 offset:2048
	ds_read_b128 v[206:209], v153 offset:3072
	ds_read_b128 v[210:213], v153 offset:4096
	ds_read_b128 v[214:217], v153 offset:5120
	ds_read_b128 v[232:235], v153 offset:6144
	ds_read_b128 v[236:239], v153 offset:7168
	global_load_lds_dwordx4 v[146:147], off
	v_lshl_add_u64 v[146:147], s[8:9], 0, v[138:139]
	s_add_i32 m0, s31, 0xe000
	s_nop 0
	global_load_lds_dwordx4 v[146:147], off
	s_waitcnt vmcnt(8)
	s_waitcnt lgkmcnt(0)
	s_barrier
	s_setprio 1
	s_waitcnt lgkmcnt(0)
	v_mfma_f32_16x16x32_bf16 v[124:127], v[142:145], v[182:185], v[124:127]
	v_mfma_f32_16x16x32_bf16 v[116:119], v[158:161], v[182:185], v[116:119]
	v_mfma_f32_16x16x32_bf16 v[108:111], v[142:145], v[202:205], v[108:111]
	v_mfma_f32_16x16x32_bf16 v[100:103], v[158:161], v[202:205], v[100:103]
	v_mfma_f32_16x16x32_bf16 v[92:95], v[142:145], v[210:213], v[92:95]
	v_mfma_f32_16x16x32_bf16 v[84:87], v[158:161], v[210:213], v[84:87]
	v_mfma_f32_16x16x32_bf16 v[76:79], v[142:145], v[232:235], v[76:79]
	v_mfma_f32_16x16x32_bf16 v[68:71], v[158:161], v[232:235], v[68:71]
	v_mfma_f32_16x16x32_bf16 v[124:127], v[154:157], v[186:189], v[124:127]
	v_mfma_f32_16x16x32_bf16 v[116:119], v[162:165], v[186:189], v[116:119]
	v_mfma_f32_16x16x32_bf16 v[108:111], v[154:157], v[206:209], v[108:111]
	v_mfma_f32_16x16x32_bf16 v[100:103], v[162:165], v[206:209], v[100:103]
	v_mfma_f32_16x16x32_bf16 v[92:95], v[154:157], v[214:217], v[92:95]
	v_mfma_f32_16x16x32_bf16 v[84:87], v[162:165], v[214:217], v[84:87]
	v_mfma_f32_16x16x32_bf16 v[76:79], v[154:157], v[236:239], v[76:79]
	v_mfma_f32_16x16x32_bf16 v[68:71], v[162:165], v[236:239], v[68:71]
	v_mfma_f32_16x16x32_bf16 v[120:123], v[166:169], v[182:185], v[120:123]
	v_mfma_f32_16x16x32_bf16 v[112:115], v[174:177], v[182:185], v[112:115]
	v_mfma_f32_16x16x32_bf16 v[104:107], v[166:169], v[202:205], v[104:107]
	v_mfma_f32_16x16x32_bf16 v[96:99], v[174:177], v[202:205], v[96:99]
	v_mfma_f32_16x16x32_bf16 v[88:91], v[166:169], v[210:213], v[88:91]
	v_mfma_f32_16x16x32_bf16 v[80:83], v[174:177], v[210:213], v[80:83]
	v_mfma_f32_16x16x32_bf16 v[72:75], v[166:169], v[232:235], v[72:75]
	v_mfma_f32_16x16x32_bf16 v[64:67], v[174:177], v[232:235], v[64:67]
	v_mfma_f32_16x16x32_bf16 v[120:123], v[170:173], v[186:189], v[120:123]
	v_mfma_f32_16x16x32_bf16 v[112:115], v[178:181], v[186:189], v[112:115]
	v_mfma_f32_16x16x32_bf16 v[104:107], v[170:173], v[206:209], v[104:107]
	v_mfma_f32_16x16x32_bf16 v[96:99], v[178:181], v[206:209], v[96:99]
	v_mfma_f32_16x16x32_bf16 v[88:91], v[170:173], v[214:217], v[88:91]
	v_mfma_f32_16x16x32_bf16 v[80:83], v[178:181], v[214:217], v[80:83]
	v_mfma_f32_16x16x32_bf16 v[72:75], v[170:173], v[236:239], v[72:75]
	v_mfma_f32_16x16x32_bf16 v[64:67], v[178:181], v[236:239], v[64:67]
	s_setprio 0
	s_barrier
	s_add_i32 s48, s48, s2
	v_lshl_add_u64 v[146:147], s[26:27], 0, v[132:133]
	s_mov_b32 m0, s48
	ds_read_b128 v[182:185], v153 offset:16384
	ds_read_b128 v[186:189], v153 offset:17408
	ds_read_b128 v[202:205], v153 offset:18432
	ds_read_b128 v[206:209], v153 offset:19456
	ds_read_b128 v[210:213], v153 offset:20480
	ds_read_b128 v[214:217], v153 offset:21504
	ds_read_b128 v[232:235], v153 offset:22528
	ds_read_b128 v[236:239], v153 offset:23552
	global_load_lds_dwordx4 v[146:147], off
	s_add_i32 m0, s48, 0x2000
	s_add_u32 s48, s26, 0x40000
	v_lshl_add_u64 v[190:191], s[26:27], 0, v[128:129]
	s_addc_u32 s49, s27, 0
	s_add_i32 s50, s50, s2
	global_load_lds_dwordx4 v[190:191], off
	v_lshl_add_u64 v[196:197], s[48:49], 0, v[132:133]
	s_mov_b32 m0, s50
	v_lshl_add_u64 v[198:199], s[28:29], 0, v[130:131]
	global_load_lds_dwordx4 v[196:197], off
	v_lshl_add_u64 v[196:197], s[48:49], 0, v[128:129]
	s_add_i32 m0, s50, 0x2000
	s_nop 0
	global_load_lds_dwordx4 v[196:197], off
	v_lshl_add_u64 v[196:197], s[28:29], 0, v[134:135]
	s_mov_b32 m0, s31
	s_nop 0
	global_load_lds_dwordx4 v[196:197], off
	s_mov_b32 m0, s34
	s_nop 0
	global_load_lds_dwordx4 v[198:199], off
	s_waitcnt vmcnt(8)
	s_waitcnt lgkmcnt(0)
	s_barrier
; #define PG8_STAGE(bufoff, gbase, voff) do { _Pragma("unroll") for (int _i = 0; _i < 2; ++_i) \
;         __builtin_amdgcn_global_load_lds((const unsigned*)((const char*)(gbase) + (voff)[_i]), (PG8_LAS unsigned*)(lds + (bufoff) + ldsw + _i * 8192), 16, 0, 0); } while (0)
; #define PG8_LDA(dst, b, h) do { _Pragma("unroll") for (int m = 0; m < 4; ++m) _Pragma("unroll") for (int k = 0; k < 2; ++k) dst[m][k] = *(const PG8_LAS bf16x8*)(lds + PG8_SA(b, h) + aoff + m * 2048 + k * 1024); } while (0)
; #define PG8_LDB(dst, b, h) do { _Pragma("unroll") for (int n = 0; n < 2; ++n) _Pragma("unroll") for (int k = 0; k < 2; ++k) dst[n][k] = *(const PG8_LAS bf16x8*)(lds + PG8_SB(b, h) + boff + n * 2048 + k * 1024); } while (0)
; #define PG8_MMA(ai, bj, At, Bt) do { __builtin_amdgcn_s_setprio(1); _Pragma("unroll") for (int m = 0; m < 4; ++m) _Pragma("unroll") for (int n = 0; n < 2; ++n) _Pragma("unroll") for (int k = 0; k < 2; ++k) \
;         acc[ai][bj][m][n] = __builtin_amdgcn_mfma_f32_16x16x32_bf16(Bt[n][k], At[m][k], acc[ai][bj][m][n], 0, 0, 0); __builtin_amdgcn_s_setprio(0); } while (0)
; #define PG8_WAIT_V(n) asm volatile("s_waitcnt vmcnt(" #n ")" ::: "memory")
; #define PG8_WAIT_L(n) asm volatile("s_waitcnt lgkmcnt(" #n ")" ::: "memory")
; #define PG8_BAR __builtin_amdgcn_s_barrier()
; #define PG8_SCHED __builtin_amdgcn_sched_barrier(0)
; template <class Epi, class Sched, bool ALIGN_EPI = false, bool SP2 = false>
; __device__ __forceinline__ void gemm_phase(PG8_LAS unsigned char* lds, const Gemm g, const Sched& S, const Epi& E) {
;     ...
;             PG8_WAIT_V(8); PG8_WAIT_L(0); PG8_BAR; PG8_MMA(1, 0, At, B0); PG8_MMA(1, 1, At, B1); PG8_BAR; PG8_SCHED;
;             PG8_LDB(B0, 1, 0); PG8_LDB(B1, 1, 1); PG8_SCHED; PG8_LDA(At, 1, 0); PG8_STAGE(PG8_SA(0, 1), a2 + hstep, voffA);
;             PG8_WAIT_V(8); PG8_WAIT_L(0); PG8_BAR; PG8_MMA(0, 0, At, B0); PG8_MMA(0, 1, At, B1); PG8_BAR; PG8_SCHED;
	s_setprio 1
	s_waitcnt lgkmcnt(0)
	v_mfma_f32_16x16x32_bf16 v[60:63], v[142:145], v[182:185], v[60:63]
	v_mfma_f32_16x16x32_bf16 v[52:55], v[158:161], v[182:185], v[52:55]
	v_mfma_f32_16x16x32_bf16 v[44:47], v[142:145], v[202:205], v[44:47]
	v_mfma_f32_16x16x32_bf16 v[36:39], v[158:161], v[202:205], v[36:39]
	v_mfma_f32_16x16x32_bf16 v[28:31], v[142:145], v[210:213], v[28:31]
	v_mfma_f32_16x16x32_bf16 v[20:23], v[158:161], v[210:213], v[20:23]
	v_mfma_f32_16x16x32_bf16 v[12:15], v[142:145], v[232:235], v[12:15]
	v_mfma_f32_16x16x32_bf16 v[4:7], v[158:161], v[232:235], v[4:7]
	v_mfma_f32_16x16x32_bf16 v[60:63], v[154:157], v[186:189], v[60:63]
	v_mfma_f32_16x16x32_bf16 v[52:55], v[162:165], v[186:189], v[52:55]
	v_mfma_f32_16x16x32_bf16 v[44:47], v[154:157], v[206:209], v[44:47]
	v_mfma_f32_16x16x32_bf16 v[36:39], v[162:165], v[206:209], v[36:39]
	v_mfma_f32_16x16x32_bf16 v[28:31], v[154:157], v[214:217], v[28:31]
	v_mfma_f32_16x16x32_bf16 v[20:23], v[162:165], v[214:217], v[20:23]
	v_mfma_f32_16x16x32_bf16 v[12:15], v[154:157], v[236:239], v[12:15]
	v_mfma_f32_16x16x32_bf16 v[4:7], v[162:165], v[236:239], v[4:7]
	v_mfma_f32_16x16x32_bf16 v[56:59], v[166:169], v[182:185], v[56:59]
	v_mfma_f32_16x16x32_bf16 v[48:51], v[174:177], v[182:185], v[48:51]
	v_mfma_f32_16x16x32_bf16 v[40:43], v[166:169], v[202:205], v[40:43]
	v_mfma_f32_16x16x32_bf16 v[32:35], v[174:177], v[202:205], v[32:35]
	v_mfma_f32_16x16x32_bf16 v[24:27], v[166:169], v[210:213], v[24:27]
	v_mfma_f32_16x16x32_bf16 v[16:19], v[174:177], v[210:213], v[16:19]
	v_mfma_f32_16x16x32_bf16 v[8:11], v[166:169], v[232:235], v[8:11]
	v_mfma_f32_16x16x32_bf16 v[0:3], v[174:177], v[232:235], v[0:3]
	v_mfma_f32_16x16x32_bf16 v[56:59], v[170:173], v[186:189], v[56:59]
	v_mfma_f32_16x16x32_bf16 v[48:51], v[178:181], v[186:189], v[48:51]
	v_mfma_f32_16x16x32_bf16 v[40:43], v[170:173], v[206:209], v[40:43]
	v_mfma_f32_16x16x32_bf16 v[32:35], v[178:181], v[206:209], v[32:35]
	v_mfma_f32_16x16x32_bf16 v[24:27], v[170:173], v[214:217], v[24:27]
	v_mfma_f32_16x16x32_bf16 v[16:19], v[178:181], v[214:217], v[16:19]
	v_mfma_f32_16x16x32_bf16 v[8:11], v[170:173], v[236:239], v[8:11]
	v_mfma_f32_16x16x32_bf16 v[0:3], v[178:181], v[236:239], v[0:3]
	s_setprio 0
	s_barrier
	s_add_i32 s48, 0, 0x18000
	v_add_u32_e32 v140, s48, v148
	s_add_i32 s49, 0, 0x1c000
	ds_read_b128 v[142:145], v140
	ds_read_b128 v[154:157], v140 offset:1024
	ds_read_b128 v[158:161], v140 offset:2048
	ds_read_b128 v[162:165], v140 offset:3072
	v_add_u32_e32 v140, s49, v148
	ds_read_b128 v[166:169], v140
	ds_read_b128 v[170:173], v140 offset:1024
	ds_read_b128 v[174:177], v140 offset:2048
	ds_read_b128 v[178:181], v140 offset:3072
	s_add_u32 s28, s28, 0x40000
	s_addc_u32 s29, s29, 0
	s_mov_b32 m0, s35
	v_lshl_add_u64 v[220:221], s[28:29], 0, v[134:135]
	ds_read_b128 v[182:185], v153 offset:32768
	ds_read_b128 v[186:189], v153 offset:33792
	ds_read_b128 v[202:205], v153 offset:34816
	ds_read_b128 v[206:209], v153 offset:35840
	ds_read_b128 v[210:213], v153 offset:36864
	ds_read_b128 v[214:217], v153 offset:37888
	ds_read_b128 v[232:235], v153 offset:38912
	ds_read_b128 v[236:239], v153 offset:39936
	global_load_lds_dwordx4 v[220:221], off
	v_lshl_add_u64 v[220:221], s[28:29], 0, v[130:131]
	s_mov_b32 m0, s36
	s_nop 0
	global_load_lds_dwordx4 v[220:221], off
	s_waitcnt vmcnt(8)
	s_waitcnt lgkmcnt(0)
	s_barrier
	s_setprio 1
	s_waitcnt lgkmcnt(0)
	v_mfma_f32_16x16x32_bf16 v[124:127], v[142:145], v[182:185], v[124:127]
	v_mfma_f32_16x16x32_bf16 v[116:119], v[158:161], v[182:185], v[116:119]
	v_mfma_f32_16x16x32_bf16 v[108:111], v[142:145], v[202:205], v[108:111]
	v_mfma_f32_16x16x32_bf16 v[100:103], v[158:161], v[202:205], v[100:103]
	v_mfma_f32_16x16x32_bf16 v[92:95], v[142:145], v[210:213], v[92:95]
	v_mfma_f32_16x16x32_bf16 v[84:87], v[158:161], v[210:213], v[84:87]
	v_mfma_f32_16x16x32_bf16 v[76:79], v[142:145], v[232:235], v[76:79]
	v_mfma_f32_16x16x32_bf16 v[68:71], v[158:161], v[232:235], v[68:71]
	v_mfma_f32_16x16x32_bf16 v[124:127], v[154:157], v[186:189], v[124:127]
	v_mfma_f32_16x16x32_bf16 v[116:119], v[162:165], v[186:189], v[116:119]
	v_mfma_f32_16x16x32_bf16 v[108:111], v[154:157], v[206:209], v[108:111]
	v_mfma_f32_16x16x32_bf16 v[100:103], v[162:165], v[206:209], v[100:103]
	v_mfma_f32_16x16x32_bf16 v[92:95], v[154:157], v[214:217], v[92:95]
	v_mfma_f32_16x16x32_bf16 v[84:87], v[162:165], v[214:217], v[84:87]
	v_mfma_f32_16x16x32_bf16 v[76:79], v[154:157], v[236:239], v[76:79]
	v_mfma_f32_16x16x32_bf16 v[68:71], v[162:165], v[236:239], v[68:71]
	v_mfma_f32_16x16x32_bf16 v[120:123], v[166:169], v[182:185], v[120:123]
	v_mfma_f32_16x16x32_bf16 v[112:115], v[174:177], v[182:185], v[112:115]
	v_mfma_f32_16x16x32_bf16 v[104:107], v[166:169], v[202:205], v[104:107]
	v_mfma_f32_16x16x32_bf16 v[96:99], v[174:177], v[202:205], v[96:99]
	v_mfma_f32_16x16x32_bf16 v[88:91], v[166:169], v[210:213], v[88:91]
	v_mfma_f32_16x16x32_bf16 v[80:83], v[174:177], v[210:213], v[80:83]
	v_mfma_f32_16x16x32_bf16 v[72:75], v[166:169], v[232:235], v[72:75]
	v_mfma_f32_16x16x32_bf16 v[64:67], v[174:177], v[232:235], v[64:67]
	v_mfma_f32_16x16x32_bf16 v[120:123], v[170:173], v[186:189], v[120:123]
	v_mfma_f32_16x16x32_bf16 v[112:115], v[178:181], v[186:189], v[112:115]
	v_mfma_f32_16x16x32_bf16 v[104:107], v[170:173], v[206:209], v[104:107]
	v_mfma_f32_16x16x32_bf16 v[96:99], v[178:181], v[206:209], v[96:99]
	v_mfma_f32_16x16x32_bf16 v[88:91], v[170:173], v[214:217], v[88:91]
	v_mfma_f32_16x16x32_bf16 v[80:83], v[178:181], v[214:217], v[80:83]
	v_mfma_f32_16x16x32_bf16 v[72:75], v[170:173], v[236:239], v[72:75]
	v_mfma_f32_16x16x32_bf16 v[64:67], v[178:181], v[236:239], v[64:67]
	s_setprio 0
	s_barrier
; #define PG8_STAGE(bufoff, gbase, voff) do { _Pragma("unroll") for (int _i = 0; _i < 2; ++_i) \
;         __builtin_amdgcn_global_load_lds((const unsigned*)((const char*)(gbase) + (voff)[_i]), (PG8_LAS unsigned*)(lds + (bufoff) + ldsw + _i * 8192), 16, 0, 0); } while (0)
; #define PG8_LDA(dst, b, h) do { _Pragma("unroll") for (int m = 0; m < 4; ++m) _Pragma("unroll") for (int k = 0; k < 2; ++k) dst[m][k] = *(const PG8_LAS bf16x8*)(lds + PG8_SA(b, h) + aoff + m * 2048 + k * 1024); } while (0)
; #define PG8_MMA(ai, bj, At, Bt) do { __builtin_amdgcn_s_setprio(1); _Pragma("unroll") for (int m = 0; m < 4; ++m) _Pragma("unroll") for (int n = 0; n < 2; ++n) _Pragma("unroll") for (int k = 0; k < 2; ++k) \
;         acc[ai][bj][m][n] = __builtin_amdgcn_mfma_f32_16x16x32_bf16(Bt[n][k], At[m][k], acc[ai][bj][m][n], 0, 0, 0); __builtin_amdgcn_s_setprio(0); } while (0)
; #define PG8_WAIT_V(n) asm volatile("s_waitcnt vmcnt(" #n ")" ::: "memory")
; #define PG8_WAIT_L(n) asm volatile("s_waitcnt lgkmcnt(" #n ")" ::: "memory")
; #define PG8_BAR __builtin_amdgcn_s_barrier()
; #define PG8_SCHED __builtin_amdgcn_sched_barrier(0)
; template <class Epi, class Sched, bool ALIGN_EPI = false, bool SP2 = false>
; __device__ __forceinline__ void gemm_phase(PG8_LAS unsigned char* lds, const Gemm g, const Sched& S, const Epi& E) {
;     ...
;         for (int t = 0; t < nt; t += 2) {
;     ...
;             PG8_LDA(At, 1, 1); PG8_STAGE(PG8_SB(1, 0), b3, voffB); PG8_STAGE(PG8_SB(1, 1), b3 + hstep, voffB); PG8_STAGE(PG8_SA(1, 0), a3, voffA);
;             PG8_WAIT_V(8); PG8_WAIT_L(0); PG8_BAR; PG8_MMA(1, 0, At, B0); PG8_MMA(1, 1, At, B1); PG8_BAR; PG8_SCHED;
	s_add_i32 s28, s48, s2
	v_lshl_add_u64 v[146:147], v[146:147], 0, s[0:1]
	s_mov_b32 m0, s28
	ds_read_b128 v[182:185], v153 offset:49152
	ds_read_b128 v[186:189], v153 offset:50176
	ds_read_b128 v[202:205], v153 offset:51200
	ds_read_b128 v[206:209], v153 offset:52224
	ds_read_b128 v[210:213], v153 offset:53248
	ds_read_b128 v[214:217], v153 offset:54272
	ds_read_b128 v[232:235], v153 offset:55296
	ds_read_b128 v[236:239], v153 offset:56320
	global_load_lds_dwordx4 v[146:147], off
	s_add_i32 m0, s28, 0x2000
	s_add_u32 s26, s26, 0x40080
	v_lshl_add_u64 v[146:147], v[190:191], 0, s[0:1]
	s_addc_u32 s27, s27, 0
	s_add_i32 s28, s49, s2
	global_load_lds_dwordx4 v[146:147], off
	v_lshl_add_u64 v[146:147], s[26:27], 0, v[132:133]
	s_mov_b32 m0, s28
	s_nop 0
	global_load_lds_dwordx4 v[146:147], off
	v_lshl_add_u64 v[146:147], s[26:27], 0, v[128:129]
	s_add_i32 m0, s28, 0x2000
	s_nop 0
	global_load_lds_dwordx4 v[146:147], off
	v_lshl_add_u64 v[146:147], v[196:197], 0, s[0:1]
	s_mov_b32 m0, s37
	s_nop 0
	global_load_lds_dwordx4 v[146:147], off
	v_lshl_add_u64 v[146:147], v[198:199], 0, s[0:1]
	s_mov_b32 m0, s38
	s_nop 0
	global_load_lds_dwordx4 v[146:147], off
	s_waitcnt vmcnt(8)
	s_waitcnt lgkmcnt(0)
	s_barrier
	s_setprio 1
	s_waitcnt lgkmcnt(0)
	v_mfma_f32_16x16x32_bf16 v[60:63], v[142:145], v[182:185], v[60:63]
	v_mfma_f32_16x16x32_bf16 v[52:55], v[158:161], v[182:185], v[52:55]
	v_mfma_f32_16x16x32_bf16 v[44:47], v[142:145], v[202:205], v[44:47]
	v_mfma_f32_16x16x32_bf16 v[36:39], v[158:161], v[202:205], v[36:39]
	v_mfma_f32_16x16x32_bf16 v[28:31], v[142:145], v[210:213], v[28:31]
	v_mfma_f32_16x16x32_bf16 v[20:23], v[158:161], v[210:213], v[20:23]
	v_mfma_f32_16x16x32_bf16 v[12:15], v[142:145], v[232:235], v[12:15]
	v_mfma_f32_16x16x32_bf16 v[4:7], v[158:161], v[232:235], v[4:7]
	v_mfma_f32_16x16x32_bf16 v[60:63], v[154:157], v[186:189], v[60:63]
	v_mfma_f32_16x16x32_bf16 v[52:55], v[162:165], v[186:189], v[52:55]
	v_mfma_f32_16x16x32_bf16 v[44:47], v[154:157], v[206:209], v[44:47]
	v_mfma_f32_16x16x32_bf16 v[36:39], v[162:165], v[206:209], v[36:39]
	v_mfma_f32_16x16x32_bf16 v[28:31], v[154:157], v[214:217], v[28:31]
	v_mfma_f32_16x16x32_bf16 v[20:23], v[162:165], v[214:217], v[20:23]
	v_mfma_f32_16x16x32_bf16 v[12:15], v[154:157], v[236:239], v[12:15]
	v_mfma_f32_16x16x32_bf16 v[4:7], v[162:165], v[236:239], v[4:7]
	v_mfma_f32_16x16x32_bf16 v[56:59], v[166:169], v[182:185], v[56:59]
	v_mfma_f32_16x16x32_bf16 v[48:51], v[174:177], v[182:185], v[48:51]
	v_mfma_f32_16x16x32_bf16 v[40:43], v[166:169], v[202:205], v[40:43]
	v_mfma_f32_16x16x32_bf16 v[32:35], v[174:177], v[202:205], v[32:35]
	v_mfma_f32_16x16x32_bf16 v[24:27], v[166:169], v[210:213], v[24:27]
	v_mfma_f32_16x16x32_bf16 v[16:19], v[174:177], v[210:213], v[16:19]
	v_mfma_f32_16x16x32_bf16 v[8:11], v[166:169], v[232:235], v[8:11]
	v_mfma_f32_16x16x32_bf16 v[0:3], v[174:177], v[232:235], v[0:3]
	v_mfma_f32_16x16x32_bf16 v[56:59], v[170:173], v[186:189], v[56:59]
	v_mfma_f32_16x16x32_bf16 v[48:51], v[178:181], v[186:189], v[48:51]
	v_mfma_f32_16x16x32_bf16 v[40:43], v[170:173], v[206:209], v[40:43]
	v_mfma_f32_16x16x32_bf16 v[32:35], v[178:181], v[206:209], v[32:35]
	v_mfma_f32_16x16x32_bf16 v[24:27], v[170:173], v[214:217], v[24:27]
	v_mfma_f32_16x16x32_bf16 v[16:19], v[178:181], v[214:217], v[16:19]
	v_mfma_f32_16x16x32_bf16 v[8:11], v[170:173], v[236:239], v[8:11]
	v_mfma_f32_16x16x32_bf16 v[0:3], v[178:181], v[236:239], v[0:3]
	s_setprio 0
	s_barrier
	s_add_i32 s47, s47, 2
	s_add_u32 s8, s8, 0x100
	s_addc_u32 s9, s9, 0
	s_add_u32 s45, s45, 0x100
	s_addc_u32 s46, s46, 0
	s_cmp_gt_u32 s47, 13
	s_cbranch_scc0 .LBB0_161
	s_and_b64 vcc, exec, s[16:17]
	s_cbranch_vccz .LBB0_164
	s_barrier

; #define PG8_STAGE(bufoff, gbase, voff) do { _Pragma("unroll") for (int _i = 0; _i < 2; ++_i) \
;         __builtin_amdgcn_global_load_lds((const unsigned*)((const char*)(gbase) + (voff)[_i]), (PG8_LAS unsigned*)(lds + (bufoff) + ldsw + _i * 8192), 16, 0, 0); } while (0)
; #define PG8_LDA(dst, b, h) do { _Pragma("unroll") for (int m = 0; m < 4; ++m) _Pragma("unroll") for (int k = 0; k < 2; ++k) dst[m][k] = *(const PG8_LAS bf16x8*)(lds + PG8_SA(b, h) + aoff + m * 2048 + k * 1024); } while (0)
; #define PG8_LDB(dst, b, h) do { _Pragma("unroll") for (int n = 0; n < 2; ++n) _Pragma("unroll") for (int k = 0; k < 2; ++k) dst[n][k] = *(const PG8_LAS bf16x8*)(lds + PG8_SB(b, h) + boff + n * 2048 + k * 1024); } while (0)
; #define PG8_MMA(ai, bj, At, Bt) do { __builtin_amdgcn_s_setprio(1); _Pragma("unroll") for (int m = 0; m < 4; ++m) _Pragma("unroll") for (int n = 0; n < 2; ++n) _Pragma("unroll") for (int k = 0; k < 2; ++k) \
;         acc[ai][bj][m][n] = __builtin_amdgcn_mfma_f32_16x16x32_bf16(Bt[n][k], At[m][k], acc[ai][bj][m][n], 0, 0, 0); __builtin_amdgcn_s_setprio(0); } while (0)
; #define PG8_WAIT_V(n) asm volatile("s_waitcnt vmcnt(" #n ")" ::: "memory")
; #define PG8_WAIT_L(n) asm volatile("s_waitcnt lgkmcnt(" #n ")" ::: "memory")
; #define PG8_BAR __builtin_amdgcn_s_barrier()
; #define PG8_SCHED __builtin_amdgcn_sched_barrier(0)
; template <class Epi, class Sched, bool ALIGN_EPI = false, bool SP2 = false>
; __device__ __forceinline__ void gemm_phase(PG8_LAS unsigned char* lds, const Gemm g, const Sched& S, const Epi& E) {
;     ...
;             PG8_LDB(B0, 0, 0); PG8_LDB(B1, 0, 1); PG8_SCHED; PG8_LDA(At, 0, 0); PG8_STAGE(PG8_SA(1, 1), a1 + hstep, voffA);
;             PG8_WAIT_V(8); PG8_WAIT_L(0); PG8_BAR; PG8_MMA(0, 0, At, B0); PG8_MMA(0, 1, At, B1); PG8_BAR; PG8_SCHED;
;             PG8_LDA(At, 0, 1); PG8_STAGE(PG8_SB(0, 0), b2, voffB); PG8_STAGE(PG8_SB(0, 1), b2 + hstep, voffB); PG8_STAGE(PG8_SA(0, 0), a2, voffA);
.LBB0_242:
	s_add_u32 s24, s22, 0x100
	s_addc_u32 s25, s23, 0
	s_add_i32 s49, 0, 0x10000
	s_cmp_eq_u32 s48, 40
	s_cselect_b32 s31, s11, s25
	s_cselect_b32 s30, s10, s24
	s_cselect_b32 s29, s21, s47
	s_cselect_b32 s28, s20, s46
	s_add_i32 s50, 0, 0x14000
	v_add_u32_e32 v124, s49, v232
	v_add_u32_e32 v156, s50, v232
	ds_read_b128 v[96:99], v124
	ds_read_b128 v[108:111], v124 offset:1024
	ds_read_b128 v[116:119], v124 offset:2048
	ds_read_b128 v[124:127], v124 offset:3072
	ds_read_b128 v[136:139], v156
	ds_read_b128 v[140:143], v156 offset:1024
	ds_read_b128 v[152:155], v156 offset:2048
	ds_read_b128 v[156:159], v156 offset:3072
	v_lshl_add_u64 v[214:215], s[22:23], 0, v[210:211]
	s_add_i32 m0, s36, 0xc000
	ds_read_b128 v[160:163], v243
	ds_read_b128 v[164:167], v243 offset:1024
	ds_read_b128 v[168:171], v243 offset:2048
	ds_read_b128 v[172:175], v243 offset:3072
	ds_read_b128 v[176:179], v243 offset:4096
	ds_read_b128 v[180:183], v243 offset:5120
	ds_read_b128 v[184:187], v243 offset:6144
	ds_read_b128 v[188:191], v243 offset:7168
	global_load_lds_dwordx4 v[214:215], off
	v_lshl_add_u64 v[214:215], s[22:23], 0, v[212:213]
	s_add_i32 m0, s36, 0xe000
	s_nop 0
	global_load_lds_dwordx4 v[214:215], off
	s_waitcnt vmcnt(8)
	s_waitcnt lgkmcnt(0)
	s_barrier
	s_setprio 1
	s_waitcnt lgkmcnt(0)
	v_mfma_f32_16x16x32_bf16 v[148:151], v[96:99], v[160:163], v[148:151]
	v_mfma_f32_16x16x32_bf16 v[144:147], v[116:119], v[160:163], v[144:147]
	v_mfma_f32_16x16x32_bf16 v[120:123], v[96:99], v[168:171], v[120:123]
	v_mfma_f32_16x16x32_bf16 v[112:115], v[116:119], v[168:171], v[112:115]
	v_mfma_f32_16x16x32_bf16 v[92:95], v[96:99], v[176:179], v[92:95]
	v_mfma_f32_16x16x32_bf16 v[88:91], v[116:119], v[176:179], v[88:91]
	v_mfma_f32_16x16x32_bf16 v[76:79], v[96:99], v[184:187], v[76:79]
	v_mfma_f32_16x16x32_bf16 v[72:75], v[116:119], v[184:187], v[72:75]
	v_mfma_f32_16x16x32_bf16 v[148:151], v[108:111], v[164:167], v[148:151]
	v_mfma_f32_16x16x32_bf16 v[144:147], v[124:127], v[164:167], v[144:147]
	v_mfma_f32_16x16x32_bf16 v[120:123], v[108:111], v[172:175], v[120:123]
	v_mfma_f32_16x16x32_bf16 v[112:115], v[124:127], v[172:175], v[112:115]
	v_mfma_f32_16x16x32_bf16 v[92:95], v[108:111], v[180:183], v[92:95]
	v_mfma_f32_16x16x32_bf16 v[88:91], v[124:127], v[180:183], v[88:91]
	v_mfma_f32_16x16x32_bf16 v[76:79], v[108:111], v[188:191], v[76:79]
	v_mfma_f32_16x16x32_bf16 v[72:75], v[124:127], v[188:191], v[72:75]
	v_mfma_f32_16x16x32_bf16 v[132:135], v[136:139], v[160:163], v[132:135]
	v_mfma_f32_16x16x32_bf16 v[128:131], v[152:155], v[160:163], v[128:131]
	v_mfma_f32_16x16x32_bf16 v[104:107], v[136:139], v[168:171], v[104:107]
	v_mfma_f32_16x16x32_bf16 v[100:103], v[152:155], v[168:171], v[100:103]
	v_mfma_f32_16x16x32_bf16 v[84:87], v[136:139], v[176:179], v[84:87]
	v_mfma_f32_16x16x32_bf16 v[80:83], v[152:155], v[176:179], v[80:83]
	v_mfma_f32_16x16x32_bf16 v[68:71], v[136:139], v[184:187], v[68:71]
	v_mfma_f32_16x16x32_bf16 v[64:67], v[152:155], v[184:187], v[64:67]
	v_mfma_f32_16x16x32_bf16 v[132:135], v[140:143], v[164:167], v[132:135]
	v_mfma_f32_16x16x32_bf16 v[128:131], v[156:159], v[164:167], v[128:131]
	v_mfma_f32_16x16x32_bf16 v[104:107], v[140:143], v[172:175], v[104:107]
	v_mfma_f32_16x16x32_bf16 v[100:103], v[156:159], v[172:175], v[100:103]
	v_mfma_f32_16x16x32_bf16 v[84:87], v[140:143], v[180:183], v[84:87]
	v_mfma_f32_16x16x32_bf16 v[80:83], v[156:159], v[180:183], v[80:83]
	v_mfma_f32_16x16x32_bf16 v[68:71], v[140:143], v[188:191], v[68:71]
	v_mfma_f32_16x16x32_bf16 v[64:67], v[156:159], v[188:191], v[64:67]
	s_setprio 0
	s_barrier
	s_add_i32 s22, s49, s35
	v_lshl_add_u64 v[214:215], s[28:29], 0, v[206:207]
	s_mov_b32 m0, s22
	ds_read_b128 v[160:163], v243 offset:16384
	ds_read_b128 v[164:167], v243 offset:17408
	ds_read_b128 v[168:171], v243 offset:18432
	ds_read_b128 v[172:175], v243 offset:19456
	ds_read_b128 v[176:179], v243 offset:20480
	ds_read_b128 v[180:183], v243 offset:21504
	ds_read_b128 v[184:187], v243 offset:22528
	ds_read_b128 v[188:191], v243 offset:23552
	global_load_lds_dwordx4 v[214:215], off
	s_add_i32 m0, s22, 0x2000
	s_add_u32 s22, s28, 0xb0000
	v_lshl_add_u64 v[216:217], s[28:29], 0, v[202:203]
	s_addc_u32 s23, s29, 0
	s_add_i32 s49, s50, s35
	global_load_lds_dwordx4 v[216:217], off
	v_lshl_add_u64 v[246:247], s[22:23], 0, v[206:207]
	s_mov_b32 m0, s49
	v_lshl_add_u64 v[248:249], s[30:31], 0, v[204:205]
	global_load_lds_dwordx4 v[246:247], off
	v_lshl_add_u64 v[246:247], s[22:23], 0, v[202:203]
	s_add_i32 m0, s49, 0x2000
	s_nop 0
	global_load_lds_dwordx4 v[246:247], off
	v_lshl_add_u64 v[246:247], s[30:31], 0, v[208:209]
	s_mov_b32 m0, s36
	s_nop 0
	global_load_lds_dwordx4 v[246:247], off
	s_mov_b32 m0, s3
	s_nop 0
	global_load_lds_dwordx4 v[248:249], off
	s_waitcnt vmcnt(8)
	s_waitcnt lgkmcnt(0)
	s_barrier
; #define PG8_STAGE(bufoff, gbase, voff) do { _Pragma("unroll") for (int _i = 0; _i < 2; ++_i) \
;         __builtin_amdgcn_global_load_lds((const unsigned*)((const char*)(gbase) + (voff)[_i]), (PG8_LAS unsigned*)(lds + (bufoff) + ldsw + _i * 8192), 16, 0, 0); } while (0)
; #define PG8_LDA(dst, b, h) do { _Pragma("unroll") for (int m = 0; m < 4; ++m) _Pragma("unroll") for (int k = 0; k < 2; ++k) dst[m][k] = *(const PG8_LAS bf16x8*)(lds + PG8_SA(b, h) + aoff + m * 2048 + k * 1024); } while (0)
; #define PG8_LDB(dst, b, h) do { _Pragma("unroll") for (int n = 0; n < 2; ++n) _Pragma("unroll") for (int k = 0; k < 2; ++k) dst[n][k] = *(const PG8_LAS bf16x8*)(lds + PG8_SB(b, h) + boff + n * 2048 + k * 1024); } while (0)
; #define PG8_MMA(ai, bj, At, Bt) do { __builtin_amdgcn_s_setprio(1); _Pragma("unroll") for (int m = 0; m < 4; ++m) _Pragma("unroll") for (int n = 0; n < 2; ++n) _Pragma("unroll") for (int k = 0; k < 2; ++k) \
;         acc[ai][bj][m][n] = __builtin_amdgcn_mfma_f32_16x16x32_bf16(Bt[n][k], At[m][k], acc[ai][bj][m][n], 0, 0, 0); __builtin_amdgcn_s_setprio(0); } while (0)
; #define PG8_WAIT_V(n) asm volatile("s_waitcnt vmcnt(" #n ")" ::: "memory")
; #define PG8_WAIT_L(n) asm volatile("s_waitcnt lgkmcnt(" #n ")" ::: "memory")
; #define PG8_BAR __builtin_amdgcn_s_barrier()
; #define PG8_SCHED __builtin_amdgcn_sched_barrier(0)
; template <class Epi, class Sched, bool ALIGN_EPI = false, bool SP2 = false>
; __device__ __forceinline__ void gemm_phase(PG8_LAS unsigned char* lds, const Gemm g, const Sched& S, const Epi& E) {
;     ...
;             PG8_WAIT_V(8); PG8_WAIT_L(0); PG8_BAR; PG8_MMA(1, 0, At, B0); PG8_MMA(1, 1, At, B1); PG8_BAR; PG8_SCHED;
;             PG8_LDB(B0, 1, 0); PG8_LDB(B1, 1, 1); PG8_SCHED; PG8_LDA(At, 1, 0); PG8_STAGE(PG8_SA(0, 1), a2 + hstep, voffA);
;             PG8_WAIT_V(8); PG8_WAIT_L(0); PG8_BAR; PG8_MMA(0, 0, At, B0); PG8_MMA(0, 1, At, B1); PG8_BAR; PG8_SCHED;
	s_setprio 1
	s_waitcnt lgkmcnt(0)
	v_mfma_f32_16x16x32_bf16 v[60:63], v[96:99], v[160:163], v[60:63]
	v_mfma_f32_16x16x32_bf16 v[56:59], v[116:119], v[160:163], v[56:59]
	v_mfma_f32_16x16x32_bf16 v[44:47], v[96:99], v[168:171], v[44:47]
	v_mfma_f32_16x16x32_bf16 v[40:43], v[116:119], v[168:171], v[40:43]
	v_mfma_f32_16x16x32_bf16 v[28:31], v[96:99], v[176:179], v[28:31]
	v_mfma_f32_16x16x32_bf16 v[24:27], v[116:119], v[176:179], v[24:27]
	v_mfma_f32_16x16x32_bf16 v[12:15], v[96:99], v[184:187], v[12:15]
	v_mfma_f32_16x16x32_bf16 v[8:11], v[116:119], v[184:187], v[8:11]
	v_mfma_f32_16x16x32_bf16 v[60:63], v[108:111], v[164:167], v[60:63]
	v_mfma_f32_16x16x32_bf16 v[56:59], v[124:127], v[164:167], v[56:59]
	v_mfma_f32_16x16x32_bf16 v[44:47], v[108:111], v[172:175], v[44:47]
	v_mfma_f32_16x16x32_bf16 v[40:43], v[124:127], v[172:175], v[40:43]
	v_mfma_f32_16x16x32_bf16 v[28:31], v[108:111], v[180:183], v[28:31]
	v_mfma_f32_16x16x32_bf16 v[24:27], v[124:127], v[180:183], v[24:27]
	v_mfma_f32_16x16x32_bf16 v[12:15], v[108:111], v[188:191], v[12:15]
	v_mfma_f32_16x16x32_bf16 v[8:11], v[124:127], v[188:191], v[8:11]
	v_mfma_f32_16x16x32_bf16 v[52:55], v[136:139], v[160:163], v[52:55]
	v_mfma_f32_16x16x32_bf16 v[48:51], v[152:155], v[160:163], v[48:51]
	v_mfma_f32_16x16x32_bf16 v[36:39], v[136:139], v[168:171], v[36:39]
	v_mfma_f32_16x16x32_bf16 v[32:35], v[152:155], v[168:171], v[32:35]
	v_mfma_f32_16x16x32_bf16 v[20:23], v[136:139], v[176:179], v[20:23]
	v_mfma_f32_16x16x32_bf16 v[16:19], v[152:155], v[176:179], v[16:19]
	v_mfma_f32_16x16x32_bf16 v[4:7], v[136:139], v[184:187], v[4:7]
	v_mfma_f32_16x16x32_bf16 v[0:3], v[152:155], v[184:187], v[0:3]
	v_mfma_f32_16x16x32_bf16 v[52:55], v[140:143], v[164:167], v[52:55]
	v_mfma_f32_16x16x32_bf16 v[48:51], v[156:159], v[164:167], v[48:51]
	v_mfma_f32_16x16x32_bf16 v[36:39], v[140:143], v[172:175], v[36:39]
	v_mfma_f32_16x16x32_bf16 v[32:35], v[156:159], v[172:175], v[32:35]
	v_mfma_f32_16x16x32_bf16 v[20:23], v[140:143], v[180:183], v[20:23]
	v_mfma_f32_16x16x32_bf16 v[16:19], v[156:159], v[180:183], v[16:19]
	v_mfma_f32_16x16x32_bf16 v[4:7], v[140:143], v[188:191], v[4:7]
	v_mfma_f32_16x16x32_bf16 v[0:3], v[156:159], v[188:191], v[0:3]
	s_setprio 0
	s_barrier
	s_add_i32 s49, 0, 0x18000
	s_add_i32 s50, 0, 0x1c000
	v_add_u32_e32 v124, s49, v232
	v_add_u32_e32 v156, s50, v232
	ds_read_b128 v[96:99], v124
	ds_read_b128 v[108:111], v124 offset:1024
	ds_read_b128 v[116:119], v124 offset:2048
	ds_read_b128 v[124:127], v124 offset:3072
	ds_read_b128 v[136:139], v156
	ds_read_b128 v[140:143], v156 offset:1024
	ds_read_b128 v[152:155], v156 offset:2048
	ds_read_b128 v[156:159], v156 offset:3072
	s_add_u32 s22, s30, 0xb0000
	s_addc_u32 s23, s31, 0
	s_mov_b32 m0, s37
	v_lshl_add_u64 v[220:221], s[22:23], 0, v[208:209]
	ds_read_b128 v[160:163], v243 offset:32768
	ds_read_b128 v[164:167], v243 offset:33792
	ds_read_b128 v[168:171], v243 offset:34816
	ds_read_b128 v[172:175], v243 offset:35840
	ds_read_b128 v[176:179], v243 offset:36864
	ds_read_b128 v[180:183], v243 offset:37888
	ds_read_b128 v[184:187], v243 offset:38912
	ds_read_b128 v[188:191], v243 offset:39936
	global_load_lds_dwordx4 v[220:221], off
	v_lshl_add_u64 v[220:221], s[22:23], 0, v[204:205]
	s_mov_b32 m0, s38
	s_nop 0
	global_load_lds_dwordx4 v[220:221], off
	s_waitcnt vmcnt(8)
	s_waitcnt lgkmcnt(0)
	s_barrier
	s_setprio 1
	s_waitcnt lgkmcnt(0)
	v_mfma_f32_16x16x32_bf16 v[148:151], v[96:99], v[160:163], v[148:151]
	v_mfma_f32_16x16x32_bf16 v[144:147], v[116:119], v[160:163], v[144:147]
	v_mfma_f32_16x16x32_bf16 v[120:123], v[96:99], v[168:171], v[120:123]
	v_mfma_f32_16x16x32_bf16 v[112:115], v[116:119], v[168:171], v[112:115]
	v_mfma_f32_16x16x32_bf16 v[92:95], v[96:99], v[176:179], v[92:95]
	v_mfma_f32_16x16x32_bf16 v[88:91], v[116:119], v[176:179], v[88:91]
	v_mfma_f32_16x16x32_bf16 v[76:79], v[96:99], v[184:187], v[76:79]
	v_mfma_f32_16x16x32_bf16 v[72:75], v[116:119], v[184:187], v[72:75]
	v_mfma_f32_16x16x32_bf16 v[148:151], v[108:111], v[164:167], v[148:151]
	v_mfma_f32_16x16x32_bf16 v[144:147], v[124:127], v[164:167], v[144:147]
	v_mfma_f32_16x16x32_bf16 v[120:123], v[108:111], v[172:175], v[120:123]
	v_mfma_f32_16x16x32_bf16 v[112:115], v[124:127], v[172:175], v[112:115]
	v_mfma_f32_16x16x32_bf16 v[92:95], v[108:111], v[180:183], v[92:95]
	v_mfma_f32_16x16x32_bf16 v[88:91], v[124:127], v[180:183], v[88:91]
	v_mfma_f32_16x16x32_bf16 v[76:79], v[108:111], v[188:191], v[76:79]
	v_mfma_f32_16x16x32_bf16 v[72:75], v[124:127], v[188:191], v[72:75]
	v_mfma_f32_16x16x32_bf16 v[132:135], v[136:139], v[160:163], v[132:135]
	v_mfma_f32_16x16x32_bf16 v[128:131], v[152:155], v[160:163], v[128:131]
	v_mfma_f32_16x16x32_bf16 v[104:107], v[136:139], v[168:171], v[104:107]
	v_mfma_f32_16x16x32_bf16 v[100:103], v[152:155], v[168:171], v[100:103]
	v_mfma_f32_16x16x32_bf16 v[84:87], v[136:139], v[176:179], v[84:87]
	v_mfma_f32_16x16x32_bf16 v[80:83], v[152:155], v[176:179], v[80:83]
	v_mfma_f32_16x16x32_bf16 v[68:71], v[136:139], v[184:187], v[68:71]
	v_mfma_f32_16x16x32_bf16 v[64:67], v[152:155], v[184:187], v[64:67]
	v_mfma_f32_16x16x32_bf16 v[132:135], v[140:143], v[164:167], v[132:135]
	v_mfma_f32_16x16x32_bf16 v[128:131], v[156:159], v[164:167], v[128:131]
	v_mfma_f32_16x16x32_bf16 v[104:107], v[140:143], v[172:175], v[104:107]
	v_mfma_f32_16x16x32_bf16 v[100:103], v[156:159], v[172:175], v[100:103]
	v_mfma_f32_16x16x32_bf16 v[84:87], v[140:143], v[180:183], v[84:87]
	v_mfma_f32_16x16x32_bf16 v[80:83], v[156:159], v[180:183], v[80:83]
	v_mfma_f32_16x16x32_bf16 v[68:71], v[140:143], v[188:191], v[68:71]
	v_mfma_f32_16x16x32_bf16 v[64:67], v[156:159], v[188:191], v[64:67]
	s_setprio 0
	s_barrier
; #define PG8_STAGE(bufoff, gbase, voff) do { _Pragma("unroll") for (int _i = 0; _i < 2; ++_i) \
;         __builtin_amdgcn_global_load_lds((const unsigned*)((const char*)(gbase) + (voff)[_i]), (PG8_LAS unsigned*)(lds + (bufoff) + ldsw + _i * 8192), 16, 0, 0); } while (0)
; #define PG8_LDA(dst, b, h) do { _Pragma("unroll") for (int m = 0; m < 4; ++m) _Pragma("unroll") for (int k = 0; k < 2; ++k) dst[m][k] = *(const PG8_LAS bf16x8*)(lds + PG8_SA(b, h) + aoff + m * 2048 + k * 1024); } while (0)
; #define PG8_MMA(ai, bj, At, Bt) do { __builtin_amdgcn_s_setprio(1); _Pragma("unroll") for (int m = 0; m < 4; ++m) _Pragma("unroll") for (int n = 0; n < 2; ++n) _Pragma("unroll") for (int k = 0; k < 2; ++k) \
;         acc[ai][bj][m][n] = __builtin_amdgcn_mfma_f32_16x16x32_bf16(Bt[n][k], At[m][k], acc[ai][bj][m][n], 0, 0, 0); __builtin_amdgcn_s_setprio(0); } while (0)
; #define PG8_WAIT_V(n) asm volatile("s_waitcnt vmcnt(" #n ")" ::: "memory")
; #define PG8_WAIT_L(n) asm volatile("s_waitcnt lgkmcnt(" #n ")" ::: "memory")
; #define PG8_BAR __builtin_amdgcn_s_barrier()
; #define PG8_SCHED __builtin_amdgcn_sched_barrier(0)
; template <class Epi, class Sched, bool ALIGN_EPI = false, bool SP2 = false>
; __device__ __forceinline__ void gemm_phase(PG8_LAS unsigned char* lds, const Gemm g, const Sched& S, const Epi& E) {
;     ...
;             PG8_LDA(At, 1, 1); PG8_STAGE(PG8_SB(1, 0), b3, voffB); PG8_STAGE(PG8_SB(1, 1), b3 + hstep, voffB); PG8_STAGE(PG8_SA(1, 0), a3, voffA);
;             PG8_WAIT_V(8); PG8_WAIT_L(0); PG8_BAR; PG8_MMA(1, 0, At, B0); PG8_MMA(1, 1, At, B1); PG8_BAR; PG8_SCHED;
;     ...
;         if constexpr (ALIGN_EPI) { if (wr == 0) PG8_BAR; }
	s_add_i32 s22, s49, s35
	v_lshl_add_u64 v[214:215], v[214:215], 0, s[0:1]
	s_mov_b32 m0, s22
	ds_read_b128 v[160:163], v243 offset:49152
	ds_read_b128 v[164:167], v243 offset:50176
	ds_read_b128 v[168:171], v243 offset:51200
	ds_read_b128 v[172:175], v243 offset:52224
	ds_read_b128 v[176:179], v243 offset:53248
	ds_read_b128 v[180:183], v243 offset:54272
	ds_read_b128 v[184:187], v243 offset:55296
	ds_read_b128 v[188:191], v243 offset:56320
	global_load_lds_dwordx4 v[214:215], off
	s_add_i32 m0, s22, 0x2000
	s_add_u32 s22, s28, 0xb0080
	v_lshl_add_u64 v[214:215], v[216:217], 0, s[0:1]
	s_addc_u32 s23, s29, 0
	s_add_i32 s28, s50, s35
	global_load_lds_dwordx4 v[214:215], off
	v_lshl_add_u64 v[214:215], s[22:23], 0, v[206:207]
	s_mov_b32 m0, s28
	s_nop 0
	global_load_lds_dwordx4 v[214:215], off
	v_lshl_add_u64 v[214:215], s[22:23], 0, v[202:203]
	s_add_i32 m0, s28, 0x2000
	s_nop 0
	global_load_lds_dwordx4 v[214:215], off
	v_lshl_add_u64 v[214:215], v[246:247], 0, s[0:1]
	s_mov_b32 m0, s39
	s_nop 0
	global_load_lds_dwordx4 v[214:215], off
	v_lshl_add_u64 v[214:215], v[248:249], 0, s[0:1]
	s_mov_b32 m0, s40
	s_nop 0
	global_load_lds_dwordx4 v[214:215], off
	s_waitcnt vmcnt(8)
	s_waitcnt lgkmcnt(0)
	s_barrier
	s_setprio 1
	s_waitcnt lgkmcnt(0)
	v_mfma_f32_16x16x32_bf16 v[60:63], v[96:99], v[160:163], v[60:63]
	v_mfma_f32_16x16x32_bf16 v[56:59], v[116:119], v[160:163], v[56:59]
	v_mfma_f32_16x16x32_bf16 v[44:47], v[96:99], v[168:171], v[44:47]
	v_mfma_f32_16x16x32_bf16 v[40:43], v[116:119], v[168:171], v[40:43]
	v_mfma_f32_16x16x32_bf16 v[28:31], v[96:99], v[176:179], v[28:31]
	v_mfma_f32_16x16x32_bf16 v[24:27], v[116:119], v[176:179], v[24:27]
	v_mfma_f32_16x16x32_bf16 v[12:15], v[96:99], v[184:187], v[12:15]
	v_mfma_f32_16x16x32_bf16 v[8:11], v[116:119], v[184:187], v[8:11]
	v_mfma_f32_16x16x32_bf16 v[60:63], v[108:111], v[164:167], v[60:63]
	v_mfma_f32_16x16x32_bf16 v[56:59], v[124:127], v[164:167], v[56:59]
	v_mfma_f32_16x16x32_bf16 v[44:47], v[108:111], v[172:175], v[44:47]
	v_mfma_f32_16x16x32_bf16 v[40:43], v[124:127], v[172:175], v[40:43]
	v_mfma_f32_16x16x32_bf16 v[28:31], v[108:111], v[180:183], v[28:31]
	v_mfma_f32_16x16x32_bf16 v[24:27], v[124:127], v[180:183], v[24:27]
	v_mfma_f32_16x16x32_bf16 v[12:15], v[108:111], v[188:191], v[12:15]
	v_mfma_f32_16x16x32_bf16 v[8:11], v[124:127], v[188:191], v[8:11]
	v_mfma_f32_16x16x32_bf16 v[52:55], v[136:139], v[160:163], v[52:55]
	v_mfma_f32_16x16x32_bf16 v[48:51], v[152:155], v[160:163], v[48:51]
	v_mfma_f32_16x16x32_bf16 v[36:39], v[136:139], v[168:171], v[36:39]
	v_mfma_f32_16x16x32_bf16 v[32:35], v[152:155], v[168:171], v[32:35]
	v_mfma_f32_16x16x32_bf16 v[20:23], v[136:139], v[176:179], v[20:23]
	v_mfma_f32_16x16x32_bf16 v[16:19], v[152:155], v[176:179], v[16:19]
	v_mfma_f32_16x16x32_bf16 v[4:7], v[136:139], v[184:187], v[4:7]
	v_mfma_f32_16x16x32_bf16 v[0:3], v[152:155], v[184:187], v[0:3]
	v_mfma_f32_16x16x32_bf16 v[52:55], v[140:143], v[164:167], v[52:55]
	v_mfma_f32_16x16x32_bf16 v[48:51], v[156:159], v[164:167], v[48:51]
	v_mfma_f32_16x16x32_bf16 v[36:39], v[140:143], v[172:175], v[36:39]
	v_mfma_f32_16x16x32_bf16 v[32:35], v[156:159], v[172:175], v[32:35]
	v_mfma_f32_16x16x32_bf16 v[20:23], v[140:143], v[180:183], v[20:23]
	v_mfma_f32_16x16x32_bf16 v[16:19], v[156:159], v[180:183], v[16:19]
	v_mfma_f32_16x16x32_bf16 v[4:7], v[140:143], v[188:191], v[4:7]
	v_mfma_f32_16x16x32_bf16 v[0:3], v[156:159], v[188:191], v[0:3]
	s_setprio 0
	s_barrier
	s_add_i32 s48, s48, 2
	s_add_u32 s46, s46, 0x100
	s_addc_u32 s47, s47, 0
	s_cmp_gt_u32 s48, 41
	s_mov_b64 s[22:23], s[24:25]
	s_cbranch_scc0 .LBB0_242
	s_and_b64 vcc, exec, s[18:19]
	s_cbranch_vccz .LBB0_245
	s_barrier

; #define PG8_STAGE(bufoff, gbase, voff) do { _Pragma("unroll") for (int _i = 0; _i < 2; ++_i) \
;         __builtin_amdgcn_global_load_lds((const unsigned*)((const char*)(gbase) + (voff)[_i]), (PG8_LAS unsigned*)(lds + (bufoff) + ldsw + _i * 8192), 16, 0, 0); } while (0)
; #define PG8_LDA(dst, b, h) do { _Pragma("unroll") for (int m = 0; m < 4; ++m) _Pragma("unroll") for (int k = 0; k < 2; ++k) dst[m][k] = *(const PG8_LAS bf16x8*)(lds + PG8_SA(b, h) + aoff + m * 2048 + k * 1024); } while (0)
; #define PG8_LDB(dst, b, h) do { _Pragma("unroll") for (int n = 0; n < 2; ++n) _Pragma("unroll") for (int k = 0; k < 2; ++k) dst[n][k] = *(const PG8_LAS bf16x8*)(lds + PG8_SB(b, h) + boff + n * 2048 + k * 1024); } while (0)
; #define PG8_MMA(ai, bj, At, Bt) do { __builtin_amdgcn_s_setprio(1); _Pragma("unroll") for (int m = 0; m < 4; ++m) _Pragma("unroll") for (int n = 0; n < 2; ++n) _Pragma("unroll") for (int k = 0; k < 2; ++k) \
;         acc[ai][bj][m][n] = __builtin_amdgcn_mfma_f32_16x16x32_bf16(Bt[n][k], At[m][k], acc[ai][bj][m][n], 0, 0, 0); __builtin_amdgcn_s_setprio(0); } while (0)
; #define PG8_WAIT_V(n) asm volatile("s_waitcnt vmcnt(" #n ")" ::: "memory")
; #define PG8_WAIT_L(n) asm volatile("s_waitcnt lgkmcnt(" #n ")" ::: "memory")
; template <class Epi, class Sched, bool ALIGN_EPI = false, bool SP2 = false>
; __device__ __forceinline__ void gemm_phase(PG8_LAS unsigned char* lds, const Gemm g, const Sched& S, const Epi& E) {
;     ...
;             const bool last = (t == nt - 2);
;             const char* a1 = cA + (size_t)(t + 1) * kstep;
;             const char* a2 = last ? nA : cA + (size_t)(t + 2) * kstep; const char* b2 = last ? nB : cB + (size_t)(t + 2) * kstep;
;             const char* a3 = a2 + kstep; const char* b3 = b2 + kstep;
;             if (last && has_next) S.a_ready(nxt);
;             if constexpr (SP2) {
;             PG8_LDB(B0, 0, 0); PG8_LDB(B1, 0, 1); PG8_SCHED; PG8_LDA(At, 0, 0); PG8_STAGE(PG8_SA(1, 1), a1 + hstep, voffA);
;             PG8_WAIT_V(8); PG8_WAIT_L(0); PG8_BAR; PG8_MMA(0, 0, At, B0); PG8_MMA(0, 1, At, B1); PG8_BAR; PG8_SCHED;
;             PG8_LDA(At, 0, 1); PG8_STAGE(PG8_SB(0, 0), b2, voffB); PG8_STAGE(PG8_SB(0, 1), b2 + hstep, voffB); PG8_STAGE(PG8_SA(0, 0), a2, voffA);
;             PG8_WAIT_V(8); PG8_WAIT_L(0); PG8_BAR; PG8_MMA(1, 0, At, B0); PG8_MMA(1, 1, At, B1); PG8_BAR; PG8_SCHED;
.LBB0_331:
	s_add_u32 s22, s8, 0xfffc0080
	s_addc_u32 s23, s9, -1
	s_add_i32 s44, 0, 0x10000
	s_cmp_eq_u32 s43, 12
	s_cselect_b32 s25, s17, s23
	s_cselect_b32 s24, s39, s22
	v_add_u32_e32 v140, s44, v144
	s_cselect_b32 s23, s15, s42
	s_cselect_b32 s22, s40, s41
	s_add_i32 s46, 0, 0x14000
	ds_read_b128 v[150:153], v140
	ds_read_b128 v[154:157], v140 offset:1024
	ds_read_b128 v[158:161], v140 offset:2048
	ds_read_b128 v[162:165], v140 offset:3072
	v_add_u32_e32 v140, s46, v144
	ds_read_b128 v[166:169], v140
	ds_read_b128 v[170:173], v140 offset:1024
	ds_read_b128 v[174:177], v140 offset:2048
	ds_read_b128 v[178:181], v140 offset:3072
	v_lshl_add_u64 v[142:143], s[8:9], 0, v[136:137]
	s_add_i32 m0, s3, 0xc000
	ds_read_b128 v[182:185], v149
	ds_read_b128 v[186:189], v149 offset:1024
	ds_read_b128 v[202:205], v149 offset:2048
	ds_read_b128 v[206:209], v149 offset:3072
	ds_read_b128 v[210:213], v149 offset:4096
	ds_read_b128 v[214:217], v149 offset:5120
	ds_read_b128 v[232:235], v149 offset:6144
	ds_read_b128 v[236:239], v149 offset:7168
	global_load_lds_dwordx4 v[142:143], off
	v_lshl_add_u64 v[142:143], s[8:9], 0, v[138:139]
	s_add_i32 m0, s3, 0xe000
	s_nop 0
	global_load_lds_dwordx4 v[142:143], off
	s_waitcnt vmcnt(8)
	s_waitcnt lgkmcnt(0)
	s_barrier
	s_setprio 1
	s_waitcnt lgkmcnt(0)
	v_mfma_f32_16x16x32_bf16 v[124:127], v[150:153], v[182:185], v[124:127]
	v_mfma_f32_16x16x32_bf16 v[120:123], v[158:161], v[182:185], v[120:123]
	v_mfma_f32_16x16x32_bf16 v[112:115], v[150:153], v[202:205], v[112:115]
	v_mfma_f32_16x16x32_bf16 v[104:107], v[158:161], v[202:205], v[104:107]
	v_mfma_f32_16x16x32_bf16 v[96:99], v[150:153], v[210:213], v[96:99]
	v_mfma_f32_16x16x32_bf16 v[88:91], v[158:161], v[210:213], v[88:91]
	v_mfma_f32_16x16x32_bf16 v[80:83], v[150:153], v[232:235], v[80:83]
	v_mfma_f32_16x16x32_bf16 v[72:75], v[158:161], v[232:235], v[72:75]
	v_mfma_f32_16x16x32_bf16 v[124:127], v[154:157], v[186:189], v[124:127]
	v_mfma_f32_16x16x32_bf16 v[120:123], v[162:165], v[186:189], v[120:123]
	v_mfma_f32_16x16x32_bf16 v[112:115], v[154:157], v[206:209], v[112:115]
	v_mfma_f32_16x16x32_bf16 v[104:107], v[162:165], v[206:209], v[104:107]
	v_mfma_f32_16x16x32_bf16 v[96:99], v[154:157], v[214:217], v[96:99]
	v_mfma_f32_16x16x32_bf16 v[88:91], v[162:165], v[214:217], v[88:91]
	v_mfma_f32_16x16x32_bf16 v[80:83], v[154:157], v[236:239], v[80:83]
	v_mfma_f32_16x16x32_bf16 v[72:75], v[162:165], v[236:239], v[72:75]
	v_mfma_f32_16x16x32_bf16 v[116:119], v[166:169], v[182:185], v[116:119]
	v_mfma_f32_16x16x32_bf16 v[108:111], v[174:177], v[182:185], v[108:111]
	v_mfma_f32_16x16x32_bf16 v[100:103], v[166:169], v[202:205], v[100:103]
	v_mfma_f32_16x16x32_bf16 v[92:95], v[174:177], v[202:205], v[92:95]
	v_mfma_f32_16x16x32_bf16 v[84:87], v[166:169], v[210:213], v[84:87]
	v_mfma_f32_16x16x32_bf16 v[76:79], v[174:177], v[210:213], v[76:79]
	v_mfma_f32_16x16x32_bf16 v[68:71], v[166:169], v[232:235], v[68:71]
	v_mfma_f32_16x16x32_bf16 v[64:67], v[174:177], v[232:235], v[64:67]
	v_mfma_f32_16x16x32_bf16 v[116:119], v[170:173], v[186:189], v[116:119]
	v_mfma_f32_16x16x32_bf16 v[108:111], v[178:181], v[186:189], v[108:111]
	v_mfma_f32_16x16x32_bf16 v[100:103], v[170:173], v[206:209], v[100:103]
	v_mfma_f32_16x16x32_bf16 v[92:95], v[178:181], v[206:209], v[92:95]
	v_mfma_f32_16x16x32_bf16 v[84:87], v[170:173], v[214:217], v[84:87]
	v_mfma_f32_16x16x32_bf16 v[76:79], v[178:181], v[214:217], v[76:79]
	v_mfma_f32_16x16x32_bf16 v[68:71], v[170:173], v[236:239], v[68:71]
	v_mfma_f32_16x16x32_bf16 v[64:67], v[178:181], v[236:239], v[64:67]
	s_setprio 0
	s_barrier
	s_add_i32 s44, s44, s2
	v_lshl_add_u64 v[142:143], s[22:23], 0, v[132:133]
	s_mov_b32 m0, s44
	ds_read_b128 v[182:185], v149 offset:16384
	ds_read_b128 v[186:189], v149 offset:17408
	ds_read_b128 v[202:205], v149 offset:18432
	ds_read_b128 v[206:209], v149 offset:19456
	ds_read_b128 v[210:213], v149 offset:20480
	ds_read_b128 v[214:217], v149 offset:21504
	ds_read_b128 v[232:235], v149 offset:22528
	ds_read_b128 v[236:239], v149 offset:23552
	global_load_lds_dwordx4 v[142:143], off
	s_add_i32 m0, s44, 0x2000
	s_add_u32 s44, s22, 0x40000
	v_lshl_add_u64 v[190:191], s[22:23], 0, v[128:129]
	s_addc_u32 s45, s23, 0
	s_add_i32 s46, s46, s2
	global_load_lds_dwordx4 v[190:191], off
	v_lshl_add_u64 v[196:197], s[44:45], 0, v[132:133]
	s_mov_b32 m0, s46
	v_lshl_add_u64 v[198:199], s[24:25], 0, v[130:131]
	global_load_lds_dwordx4 v[196:197], off
	v_lshl_add_u64 v[196:197], s[44:45], 0, v[128:129]
	s_add_i32 m0, s46, 0x2000
	s_nop 0
	global_load_lds_dwordx4 v[196:197], off
	v_lshl_add_u64 v[196:197], s[24:25], 0, v[134:135]
	s_mov_b32 m0, s3
	s_nop 0
	global_load_lds_dwordx4 v[196:197], off
	s_mov_b32 m0, s28
	s_nop 0
	global_load_lds_dwordx4 v[198:199], off
	s_waitcnt vmcnt(8)
	s_waitcnt lgkmcnt(0)
	s_barrier
; #define PG8_STAGE(bufoff, gbase, voff) do { _Pragma("unroll") for (int _i = 0; _i < 2; ++_i) \
;         __builtin_amdgcn_global_load_lds((const unsigned*)((const char*)(gbase) + (voff)[_i]), (PG8_LAS unsigned*)(lds + (bufoff) + ldsw + _i * 8192), 16, 0, 0); } while (0)
; #define PG8_LDA(dst, b, h) do { _Pragma("unroll") for (int m = 0; m < 4; ++m) _Pragma("unroll") for (int k = 0; k < 2; ++k) dst[m][k] = *(const PG8_LAS bf16x8*)(lds + PG8_SA(b, h) + aoff + m * 2048 + k * 1024); } while (0)
; #define PG8_LDB(dst, b, h) do { _Pragma("unroll") for (int n = 0; n < 2; ++n) _Pragma("unroll") for (int k = 0; k < 2; ++k) dst[n][k] = *(const PG8_LAS bf16x8*)(lds + PG8_SB(b, h) + boff + n * 2048 + k * 1024); } while (0)
; #define PG8_MMA(ai, bj, At, Bt) do { __builtin_amdgcn_s_setprio(1); _Pragma("unroll") for (int m = 0; m < 4; ++m) _Pragma("unroll") for (int n = 0; n < 2; ++n) _Pragma("unroll") for (int k = 0; k < 2; ++k) \
;         acc[ai][bj][m][n] = __builtin_amdgcn_mfma_f32_16x16x32_bf16(Bt[n][k], At[m][k], acc[ai][bj][m][n], 0, 0, 0); __builtin_amdgcn_s_setprio(0); } while (0)
; #define PG8_WAIT_V(n) asm volatile("s_waitcnt vmcnt(" #n ")" ::: "memory")
; #define PG8_WAIT_L(n) asm volatile("s_waitcnt lgkmcnt(" #n ")" ::: "memory")
; #define PG8_BAR __builtin_amdgcn_s_barrier()
; #define PG8_SCHED __builtin_amdgcn_sched_barrier(0)
; template <class Epi, class Sched, bool ALIGN_EPI = false, bool SP2 = false>
; __device__ __forceinline__ void gemm_phase(PG8_LAS unsigned char* lds, const Gemm g, const Sched& S, const Epi& E) {
;     ...
;             PG8_WAIT_V(8); PG8_WAIT_L(0); PG8_BAR; PG8_MMA(1, 0, At, B0); PG8_MMA(1, 1, At, B1); PG8_BAR; PG8_SCHED;
;             PG8_LDB(B0, 1, 0); PG8_LDB(B1, 1, 1); PG8_SCHED; PG8_LDA(At, 1, 0); PG8_STAGE(PG8_SA(0, 1), a2 + hstep, voffA);
;             PG8_WAIT_V(8); PG8_WAIT_L(0); PG8_BAR; PG8_MMA(0, 0, At, B0); PG8_MMA(0, 1, At, B1); PG8_BAR; PG8_SCHED;
	s_setprio 1
	s_waitcnt lgkmcnt(0)
	v_mfma_f32_16x16x32_bf16 v[60:63], v[150:153], v[182:185], v[60:63]
	v_mfma_f32_16x16x32_bf16 v[56:59], v[158:161], v[182:185], v[56:59]
	v_mfma_f32_16x16x32_bf16 v[48:51], v[150:153], v[202:205], v[48:51]
	v_mfma_f32_16x16x32_bf16 v[40:43], v[158:161], v[202:205], v[40:43]
	v_mfma_f32_16x16x32_bf16 v[32:35], v[150:153], v[210:213], v[32:35]
	v_mfma_f32_16x16x32_bf16 v[24:27], v[158:161], v[210:213], v[24:27]
	v_mfma_f32_16x16x32_bf16 v[16:19], v[150:153], v[232:235], v[16:19]
	v_mfma_f32_16x16x32_bf16 v[8:11], v[158:161], v[232:235], v[8:11]
	v_mfma_f32_16x16x32_bf16 v[60:63], v[154:157], v[186:189], v[60:63]
	v_mfma_f32_16x16x32_bf16 v[56:59], v[162:165], v[186:189], v[56:59]
	v_mfma_f32_16x16x32_bf16 v[48:51], v[154:157], v[206:209], v[48:51]
	v_mfma_f32_16x16x32_bf16 v[40:43], v[162:165], v[206:209], v[40:43]
	v_mfma_f32_16x16x32_bf16 v[32:35], v[154:157], v[214:217], v[32:35]
	v_mfma_f32_16x16x32_bf16 v[24:27], v[162:165], v[214:217], v[24:27]
	v_mfma_f32_16x16x32_bf16 v[16:19], v[154:157], v[236:239], v[16:19]
	v_mfma_f32_16x16x32_bf16 v[8:11], v[162:165], v[236:239], v[8:11]
	v_mfma_f32_16x16x32_bf16 v[52:55], v[166:169], v[182:185], v[52:55]
	v_mfma_f32_16x16x32_bf16 v[44:47], v[174:177], v[182:185], v[44:47]
	v_mfma_f32_16x16x32_bf16 v[36:39], v[166:169], v[202:205], v[36:39]
	v_mfma_f32_16x16x32_bf16 v[28:31], v[174:177], v[202:205], v[28:31]
	v_mfma_f32_16x16x32_bf16 v[20:23], v[166:169], v[210:213], v[20:23]
	v_mfma_f32_16x16x32_bf16 v[12:15], v[174:177], v[210:213], v[12:15]
	v_mfma_f32_16x16x32_bf16 v[4:7], v[166:169], v[232:235], v[4:7]
	v_mfma_f32_16x16x32_bf16 v[0:3], v[174:177], v[232:235], v[0:3]
	v_mfma_f32_16x16x32_bf16 v[52:55], v[170:173], v[186:189], v[52:55]
	v_mfma_f32_16x16x32_bf16 v[44:47], v[178:181], v[186:189], v[44:47]
	v_mfma_f32_16x16x32_bf16 v[36:39], v[170:173], v[206:209], v[36:39]
	v_mfma_f32_16x16x32_bf16 v[28:31], v[178:181], v[206:209], v[28:31]
	v_mfma_f32_16x16x32_bf16 v[20:23], v[170:173], v[214:217], v[20:23]
	v_mfma_f32_16x16x32_bf16 v[12:15], v[178:181], v[214:217], v[12:15]
	v_mfma_f32_16x16x32_bf16 v[4:7], v[170:173], v[236:239], v[4:7]
	v_mfma_f32_16x16x32_bf16 v[0:3], v[178:181], v[236:239], v[0:3]
	s_setprio 0
	s_barrier
	s_add_i32 s44, 0, 0x18000
	v_add_u32_e32 v140, s44, v144
	s_add_i32 s45, 0, 0x1c000
	ds_read_b128 v[150:153], v140
	ds_read_b128 v[154:157], v140 offset:1024
	ds_read_b128 v[158:161], v140 offset:2048
	ds_read_b128 v[162:165], v140 offset:3072
	v_add_u32_e32 v140, s45, v144
	ds_read_b128 v[166:169], v140
	ds_read_b128 v[170:173], v140 offset:1024
	ds_read_b128 v[174:177], v140 offset:2048
	ds_read_b128 v[178:181], v140 offset:3072
	s_add_u32 s24, s24, 0x40000
	s_addc_u32 s25, s25, 0
	s_mov_b32 m0, s29
	v_lshl_add_u64 v[220:221], s[24:25], 0, v[134:135]
	ds_read_b128 v[182:185], v149 offset:32768
	ds_read_b128 v[186:189], v149 offset:33792
	ds_read_b128 v[202:205], v149 offset:34816
	ds_read_b128 v[206:209], v149 offset:35840
	ds_read_b128 v[210:213], v149 offset:36864
	ds_read_b128 v[214:217], v149 offset:37888
	ds_read_b128 v[232:235], v149 offset:38912
	ds_read_b128 v[236:239], v149 offset:39936
	global_load_lds_dwordx4 v[220:221], off
	v_lshl_add_u64 v[220:221], s[24:25], 0, v[130:131]
	s_mov_b32 m0, s30
	s_nop 0
	global_load_lds_dwordx4 v[220:221], off
	s_waitcnt vmcnt(8)
	s_waitcnt lgkmcnt(0)
	s_barrier
	s_setprio 1
	s_waitcnt lgkmcnt(0)
	v_mfma_f32_16x16x32_bf16 v[124:127], v[150:153], v[182:185], v[124:127]
	v_mfma_f32_16x16x32_bf16 v[120:123], v[158:161], v[182:185], v[120:123]
	v_mfma_f32_16x16x32_bf16 v[112:115], v[150:153], v[202:205], v[112:115]
	v_mfma_f32_16x16x32_bf16 v[104:107], v[158:161], v[202:205], v[104:107]
	v_mfma_f32_16x16x32_bf16 v[96:99], v[150:153], v[210:213], v[96:99]
	v_mfma_f32_16x16x32_bf16 v[88:91], v[158:161], v[210:213], v[88:91]
	v_mfma_f32_16x16x32_bf16 v[80:83], v[150:153], v[232:235], v[80:83]
	v_mfma_f32_16x16x32_bf16 v[72:75], v[158:161], v[232:235], v[72:75]
	v_mfma_f32_16x16x32_bf16 v[124:127], v[154:157], v[186:189], v[124:127]
	v_mfma_f32_16x16x32_bf16 v[120:123], v[162:165], v[186:189], v[120:123]
	v_mfma_f32_16x16x32_bf16 v[112:115], v[154:157], v[206:209], v[112:115]
	v_mfma_f32_16x16x32_bf16 v[104:107], v[162:165], v[206:209], v[104:107]
	v_mfma_f32_16x16x32_bf16 v[96:99], v[154:157], v[214:217], v[96:99]
	v_mfma_f32_16x16x32_bf16 v[88:91], v[162:165], v[214:217], v[88:91]
	v_mfma_f32_16x16x32_bf16 v[80:83], v[154:157], v[236:239], v[80:83]
	v_mfma_f32_16x16x32_bf16 v[72:75], v[162:165], v[236:239], v[72:75]
	v_mfma_f32_16x16x32_bf16 v[116:119], v[166:169], v[182:185], v[116:119]
	v_mfma_f32_16x16x32_bf16 v[108:111], v[174:177], v[182:185], v[108:111]
	v_mfma_f32_16x16x32_bf16 v[100:103], v[166:169], v[202:205], v[100:103]
	v_mfma_f32_16x16x32_bf16 v[92:95], v[174:177], v[202:205], v[92:95]
	v_mfma_f32_16x16x32_bf16 v[84:87], v[166:169], v[210:213], v[84:87]
	v_mfma_f32_16x16x32_bf16 v[76:79], v[174:177], v[210:213], v[76:79]
	v_mfma_f32_16x16x32_bf16 v[68:71], v[166:169], v[232:235], v[68:71]
	v_mfma_f32_16x16x32_bf16 v[64:67], v[174:177], v[232:235], v[64:67]
	v_mfma_f32_16x16x32_bf16 v[116:119], v[170:173], v[186:189], v[116:119]
	v_mfma_f32_16x16x32_bf16 v[108:111], v[178:181], v[186:189], v[108:111]
	v_mfma_f32_16x16x32_bf16 v[100:103], v[170:173], v[206:209], v[100:103]
	v_mfma_f32_16x16x32_bf16 v[92:95], v[178:181], v[206:209], v[92:95]
	v_mfma_f32_16x16x32_bf16 v[84:87], v[170:173], v[214:217], v[84:87]
	v_mfma_f32_16x16x32_bf16 v[76:79], v[178:181], v[214:217], v[76:79]
	v_mfma_f32_16x16x32_bf16 v[68:71], v[170:173], v[236:239], v[68:71]
	v_mfma_f32_16x16x32_bf16 v[64:67], v[178:181], v[236:239], v[64:67]
	s_setprio 0
	s_barrier
; #define PG8_STAGE(bufoff, gbase, voff) do { _Pragma("unroll") for (int _i = 0; _i < 2; ++_i) \
;         __builtin_amdgcn_global_load_lds((const unsigned*)((const char*)(gbase) + (voff)[_i]), (PG8_LAS unsigned*)(lds + (bufoff) + ldsw + _i * 8192), 16, 0, 0); } while (0)
; #define PG8_LDA(dst, b, h) do { _Pragma("unroll") for (int m = 0; m < 4; ++m) _Pragma("unroll") for (int k = 0; k < 2; ++k) dst[m][k] = *(const PG8_LAS bf16x8*)(lds + PG8_SA(b, h) + aoff + m * 2048 + k * 1024); } while (0)
; #define PG8_MMA(ai, bj, At, Bt) do { __builtin_amdgcn_s_setprio(1); _Pragma("unroll") for (int m = 0; m < 4; ++m) _Pragma("unroll") for (int n = 0; n < 2; ++n) _Pragma("unroll") for (int k = 0; k < 2; ++k) \
;         acc[ai][bj][m][n] = __builtin_amdgcn_mfma_f32_16x16x32_bf16(Bt[n][k], At[m][k], acc[ai][bj][m][n], 0, 0, 0); __builtin_amdgcn_s_setprio(0); } while (0)
; #define PG8_WAIT_V(n) asm volatile("s_waitcnt vmcnt(" #n ")" ::: "memory")
; #define PG8_WAIT_L(n) asm volatile("s_waitcnt lgkmcnt(" #n ")" ::: "memory")
; #define PG8_BAR __builtin_amdgcn_s_barrier()
; #define PG8_SCHED __builtin_amdgcn_sched_barrier(0)
; template <class Epi, class Sched, bool ALIGN_EPI = false, bool SP2 = false>
; __device__ __forceinline__ void gemm_phase(PG8_LAS unsigned char* lds, const Gemm g, const Sched& S, const Epi& E) {
;     ...
;             PG8_LDA(At, 1, 1); PG8_STAGE(PG8_SB(1, 0), b3, voffB); PG8_STAGE(PG8_SB(1, 1), b3 + hstep, voffB); PG8_STAGE(PG8_SA(1, 0), a3, voffA);
;             PG8_WAIT_V(8); PG8_WAIT_L(0); PG8_BAR; PG8_MMA(1, 0, At, B0); PG8_MMA(1, 1, At, B1); PG8_BAR; PG8_SCHED;
;     ...
;         if constexpr (ALIGN_EPI) { if (wr == 0) PG8_BAR; }
	s_add_i32 s24, s44, s2
	v_lshl_add_u64 v[142:143], v[142:143], 0, s[0:1]
	s_mov_b32 m0, s24
	ds_read_b128 v[182:185], v149 offset:49152
	ds_read_b128 v[186:189], v149 offset:50176
	ds_read_b128 v[202:205], v149 offset:51200
	ds_read_b128 v[206:209], v149 offset:52224
	ds_read_b128 v[210:213], v149 offset:53248
	ds_read_b128 v[214:217], v149 offset:54272
	ds_read_b128 v[232:235], v149 offset:55296
	ds_read_b128 v[236:239], v149 offset:56320
	global_load_lds_dwordx4 v[142:143], off
	s_add_i32 m0, s24, 0x2000
	s_add_u32 s22, s22, 0x40080
	v_lshl_add_u64 v[142:143], v[190:191], 0, s[0:1]
	s_addc_u32 s23, s23, 0
	s_add_i32 s24, s45, s2
	global_load_lds_dwordx4 v[142:143], off
	v_lshl_add_u64 v[142:143], s[22:23], 0, v[132:133]
	s_mov_b32 m0, s24
	s_nop 0
	global_load_lds_dwordx4 v[142:143], off
	v_lshl_add_u64 v[142:143], s[22:23], 0, v[128:129]
	s_add_i32 m0, s24, 0x2000
	s_nop 0
	global_load_lds_dwordx4 v[142:143], off
	v_lshl_add_u64 v[142:143], v[196:197], 0, s[0:1]
	s_mov_b32 m0, s31
	s_nop 0
	global_load_lds_dwordx4 v[142:143], off
	v_lshl_add_u64 v[142:143], v[198:199], 0, s[0:1]
	s_mov_b32 m0, s34
	s_nop 0
	global_load_lds_dwordx4 v[142:143], off
	s_waitcnt vmcnt(8)
	s_waitcnt lgkmcnt(0)
	s_barrier
	s_setprio 1
	s_waitcnt lgkmcnt(0)
	v_mfma_f32_16x16x32_bf16 v[60:63], v[150:153], v[182:185], v[60:63]
	v_mfma_f32_16x16x32_bf16 v[56:59], v[158:161], v[182:185], v[56:59]
	v_mfma_f32_16x16x32_bf16 v[48:51], v[150:153], v[202:205], v[48:51]
	v_mfma_f32_16x16x32_bf16 v[40:43], v[158:161], v[202:205], v[40:43]
	v_mfma_f32_16x16x32_bf16 v[32:35], v[150:153], v[210:213], v[32:35]
	v_mfma_f32_16x16x32_bf16 v[24:27], v[158:161], v[210:213], v[24:27]
	v_mfma_f32_16x16x32_bf16 v[16:19], v[150:153], v[232:235], v[16:19]
	v_mfma_f32_16x16x32_bf16 v[8:11], v[158:161], v[232:235], v[8:11]
	v_mfma_f32_16x16x32_bf16 v[60:63], v[154:157], v[186:189], v[60:63]
	v_mfma_f32_16x16x32_bf16 v[56:59], v[162:165], v[186:189], v[56:59]
	v_mfma_f32_16x16x32_bf16 v[48:51], v[154:157], v[206:209], v[48:51]
	v_mfma_f32_16x16x32_bf16 v[40:43], v[162:165], v[206:209], v[40:43]
	v_mfma_f32_16x16x32_bf16 v[32:35], v[154:157], v[214:217], v[32:35]
	v_mfma_f32_16x16x32_bf16 v[24:27], v[162:165], v[214:217], v[24:27]
	v_mfma_f32_16x16x32_bf16 v[16:19], v[154:157], v[236:239], v[16:19]
	v_mfma_f32_16x16x32_bf16 v[8:11], v[162:165], v[236:239], v[8:11]
	v_mfma_f32_16x16x32_bf16 v[52:55], v[166:169], v[182:185], v[52:55]
	v_mfma_f32_16x16x32_bf16 v[44:47], v[174:177], v[182:185], v[44:47]
	v_mfma_f32_16x16x32_bf16 v[36:39], v[166:169], v[202:205], v[36:39]
	v_mfma_f32_16x16x32_bf16 v[28:31], v[174:177], v[202:205], v[28:31]
	v_mfma_f32_16x16x32_bf16 v[20:23], v[166:169], v[210:213], v[20:23]
	v_mfma_f32_16x16x32_bf16 v[12:15], v[174:177], v[210:213], v[12:15]
	v_mfma_f32_16x16x32_bf16 v[4:7], v[166:169], v[232:235], v[4:7]
	v_mfma_f32_16x16x32_bf16 v[0:3], v[174:177], v[232:235], v[0:3]
	v_mfma_f32_16x16x32_bf16 v[52:55], v[170:173], v[186:189], v[52:55]
	v_mfma_f32_16x16x32_bf16 v[44:47], v[178:181], v[186:189], v[44:47]
	v_mfma_f32_16x16x32_bf16 v[36:39], v[170:173], v[206:209], v[36:39]
	v_mfma_f32_16x16x32_bf16 v[28:31], v[178:181], v[206:209], v[28:31]
	v_mfma_f32_16x16x32_bf16 v[20:23], v[170:173], v[214:217], v[20:23]
	v_mfma_f32_16x16x32_bf16 v[12:15], v[178:181], v[214:217], v[12:15]
	v_mfma_f32_16x16x32_bf16 v[4:7], v[170:173], v[236:239], v[4:7]
	v_mfma_f32_16x16x32_bf16 v[0:3], v[178:181], v[236:239], v[0:3]
	s_setprio 0
	s_barrier
	s_add_i32 s43, s43, 2
	s_add_u32 s8, s8, 0x100
	s_addc_u32 s9, s9, 0
	s_add_u32 s41, s41, 0x100
	s_addc_u32 s42, s42, 0
	s_cmp_gt_u32 s43, 13
	s_cbranch_scc0 .LBB0_331
	s_and_b64 vcc, exec, s[12:13]
	s_cbranch_vccz .LBB0_334
	s_barrier

; #define PG8_STAGE(bufoff, gbase, voff) do { _Pragma("unroll") for (int _i = 0; _i < 2; ++_i) \
;         __builtin_amdgcn_global_load_lds((const unsigned*)((const char*)(gbase) + (voff)[_i]), (PG8_LAS unsigned*)(lds + (bufoff) + ldsw + _i * 8192), 16, 0, 0); } while (0)
; #define PG8_LDA(dst, b, h) do { _Pragma("unroll") for (int m = 0; m < 4; ++m) _Pragma("unroll") for (int k = 0; k < 2; ++k) dst[m][k] = *(const PG8_LAS bf16x8*)(lds + PG8_SA(b, h) + aoff + m * 2048 + k * 1024); } while (0)
; #define PG8_LDB(dst, b, h) do { _Pragma("unroll") for (int n = 0; n < 2; ++n) _Pragma("unroll") for (int k = 0; k < 2; ++k) dst[n][k] = *(const PG8_LAS bf16x8*)(lds + PG8_SB(b, h) + boff + n * 2048 + k * 1024); } while (0)
; #define PG8_MMA(ai, bj, At, Bt) do { __builtin_amdgcn_s_setprio(1); _Pragma("unroll") for (int m = 0; m < 4; ++m) _Pragma("unroll") for (int n = 0; n < 2; ++n) _Pragma("unroll") for (int k = 0; k < 2; ++k) \
;         acc[ai][bj][m][n] = __builtin_amdgcn_mfma_f32_16x16x32_bf16(Bt[n][k], At[m][k], acc[ai][bj][m][n], 0, 0, 0); __builtin_amdgcn_s_setprio(0); } while (0)
; #define PG8_WAIT_V(n) asm volatile("s_waitcnt vmcnt(" #n ")" ::: "memory")
; #define PG8_WAIT_L(n) asm volatile("s_waitcnt lgkmcnt(" #n ")" ::: "memory")
; template <class Epi, class Sched, bool ALIGN_EPI = false, bool SP2 = false>
; __device__ __forceinline__ void gemm_phase(PG8_LAS unsigned char* lds, const Gemm g, const Sched& S, const Epi& E) {
;     ...
;             const bool last = (t == nt - 2);
;             const char* a1 = cA + (size_t)(t + 1) * kstep;
;             const char* a2 = last ? nA : cA + (size_t)(t + 2) * kstep; const char* b2 = last ? nB : cB + (size_t)(t + 2) * kstep;
;             const char* a3 = a2 + kstep; const char* b3 = b2 + kstep;
;             if (last && has_next) S.a_ready(nxt);
;             if constexpr (SP2) {
;             PG8_LDB(B0, 0, 0); PG8_LDB(B1, 0, 1); PG8_SCHED; PG8_LDA(At, 0, 0); PG8_STAGE(PG8_SA(1, 1), a1 + hstep, voffA);
;             PG8_WAIT_V(8); PG8_WAIT_L(0); PG8_BAR; PG8_MMA(0, 0, At, B0); PG8_MMA(0, 1, At, B1); PG8_BAR; PG8_SCHED;
;             PG8_LDA(At, 0, 1); PG8_STAGE(PG8_SB(0, 0), b2, voffB); PG8_STAGE(PG8_SB(0, 1), b2 + hstep, voffB); PG8_STAGE(PG8_SA(0, 0), a2, voffA);
;             PG8_WAIT_V(8); PG8_WAIT_L(0); PG8_BAR; PG8_MMA(1, 0, At, B0); PG8_MMA(1, 1, At, B1); PG8_BAR; PG8_SCHED;
.LBB0_1209:
	s_add_u32 s24, s22, 0xfffc0080
	s_addc_u32 s25, s23, -1
	s_add_i32 s43, 0, 0x10000
	s_cmp_eq_u32 s42, 12
	s_cselect_b32 s27, s17, s25
	s_cselect_b32 s26, s38, s24
	s_cselect_b32 s25, s15, s41
	s_cselect_b32 s24, s39, s40
	s_add_i32 s46, 0, 0x14000
	v_add_u32_e32 v124, s43, v232
	v_add_u32_e32 v156, s46, v232
	ds_read_b128 v[96:99], v124
	ds_read_b128 v[108:111], v124 offset:1024
	ds_read_b128 v[120:123], v124 offset:2048
	ds_read_b128 v[124:127], v124 offset:3072
	ds_read_b128 v[136:139], v156
	ds_read_b128 v[140:143], v156 offset:1024
	ds_read_b128 v[152:155], v156 offset:2048
	ds_read_b128 v[156:159], v156 offset:3072
	v_lshl_add_u64 v[196:197], s[22:23], 0, v[210:211]
	s_add_i32 m0, s28, 0xc000
	ds_read_b128 v[160:163], v243
	ds_read_b128 v[164:167], v243 offset:1024
	ds_read_b128 v[168:171], v243 offset:2048
	ds_read_b128 v[172:175], v243 offset:3072
	ds_read_b128 v[176:179], v243 offset:4096
	ds_read_b128 v[180:183], v243 offset:5120
	ds_read_b128 v[184:187], v243 offset:6144
	ds_read_b128 v[188:191], v243 offset:7168
	global_load_lds_dwordx4 v[196:197], off
	v_lshl_add_u64 v[196:197], s[22:23], 0, v[212:213]
	s_add_i32 m0, s28, 0xe000
	s_nop 0
	global_load_lds_dwordx4 v[196:197], off
	s_waitcnt vmcnt(8)
	s_waitcnt lgkmcnt(0)
	s_barrier
	s_setprio 1
	s_waitcnt lgkmcnt(0)
	v_mfma_f32_16x16x32_bf16 v[148:151], v[96:99], v[160:163], v[148:151]
	v_mfma_f32_16x16x32_bf16 v[144:147], v[120:123], v[160:163], v[144:147]
	v_mfma_f32_16x16x32_bf16 v[116:119], v[96:99], v[168:171], v[116:119]
	v_mfma_f32_16x16x32_bf16 v[112:115], v[120:123], v[168:171], v[112:115]
	v_mfma_f32_16x16x32_bf16 v[92:95], v[96:99], v[176:179], v[92:95]
	v_mfma_f32_16x16x32_bf16 v[88:91], v[120:123], v[176:179], v[88:91]
	v_mfma_f32_16x16x32_bf16 v[76:79], v[96:99], v[184:187], v[76:79]
	v_mfma_f32_16x16x32_bf16 v[72:75], v[120:123], v[184:187], v[72:75]
	v_mfma_f32_16x16x32_bf16 v[148:151], v[108:111], v[164:167], v[148:151]
	v_mfma_f32_16x16x32_bf16 v[144:147], v[124:127], v[164:167], v[144:147]
	v_mfma_f32_16x16x32_bf16 v[116:119], v[108:111], v[172:175], v[116:119]
	v_mfma_f32_16x16x32_bf16 v[112:115], v[124:127], v[172:175], v[112:115]
	v_mfma_f32_16x16x32_bf16 v[92:95], v[108:111], v[180:183], v[92:95]
	v_mfma_f32_16x16x32_bf16 v[88:91], v[124:127], v[180:183], v[88:91]
	v_mfma_f32_16x16x32_bf16 v[76:79], v[108:111], v[188:191], v[76:79]
	v_mfma_f32_16x16x32_bf16 v[72:75], v[124:127], v[188:191], v[72:75]
	v_mfma_f32_16x16x32_bf16 v[132:135], v[136:139], v[160:163], v[132:135]
	v_mfma_f32_16x16x32_bf16 v[128:131], v[152:155], v[160:163], v[128:131]
	v_mfma_f32_16x16x32_bf16 v[104:107], v[136:139], v[168:171], v[104:107]
	v_mfma_f32_16x16x32_bf16 v[100:103], v[152:155], v[168:171], v[100:103]
	v_mfma_f32_16x16x32_bf16 v[84:87], v[136:139], v[176:179], v[84:87]
	v_mfma_f32_16x16x32_bf16 v[80:83], v[152:155], v[176:179], v[80:83]
	v_mfma_f32_16x16x32_bf16 v[68:71], v[136:139], v[184:187], v[68:71]
	v_mfma_f32_16x16x32_bf16 v[64:67], v[152:155], v[184:187], v[64:67]
	v_mfma_f32_16x16x32_bf16 v[132:135], v[140:143], v[164:167], v[132:135]
	v_mfma_f32_16x16x32_bf16 v[128:131], v[156:159], v[164:167], v[128:131]
	v_mfma_f32_16x16x32_bf16 v[104:107], v[140:143], v[172:175], v[104:107]
	v_mfma_f32_16x16x32_bf16 v[100:103], v[156:159], v[172:175], v[100:103]
	v_mfma_f32_16x16x32_bf16 v[84:87], v[140:143], v[180:183], v[84:87]
	v_mfma_f32_16x16x32_bf16 v[80:83], v[156:159], v[180:183], v[80:83]
	v_mfma_f32_16x16x32_bf16 v[68:71], v[140:143], v[188:191], v[68:71]
	v_mfma_f32_16x16x32_bf16 v[64:67], v[156:159], v[188:191], v[64:67]
	s_setprio 0
	s_barrier
	s_add_i32 s43, s43, s2
	v_lshl_add_u64 v[196:197], s[24:25], 0, v[206:207]
	s_mov_b32 m0, s43
	ds_read_b128 v[160:163], v243 offset:16384
	ds_read_b128 v[164:167], v243 offset:17408
	ds_read_b128 v[168:171], v243 offset:18432
	ds_read_b128 v[172:175], v243 offset:19456
	ds_read_b128 v[176:179], v243 offset:20480
	ds_read_b128 v[180:183], v243 offset:21504
	ds_read_b128 v[184:187], v243 offset:22528
	ds_read_b128 v[188:191], v243 offset:23552
	global_load_lds_dwordx4 v[196:197], off
	s_add_i32 m0, s43, 0x2000
	s_add_u32 s44, s24, 0x40000
	v_lshl_add_u64 v[198:199], s[24:25], 0, v[202:203]
	s_addc_u32 s45, s25, 0
	s_add_i32 s43, s46, s2
	global_load_lds_dwordx4 v[198:199], off
	v_lshl_add_u64 v[214:215], s[44:45], 0, v[206:207]
	s_mov_b32 m0, s43
	v_lshl_add_u64 v[216:217], s[26:27], 0, v[204:205]
	global_load_lds_dwordx4 v[214:215], off
	v_lshl_add_u64 v[214:215], s[44:45], 0, v[202:203]
	s_add_i32 m0, s43, 0x2000
	s_nop 0
	global_load_lds_dwordx4 v[214:215], off
	v_lshl_add_u64 v[214:215], s[26:27], 0, v[208:209]
	s_mov_b32 m0, s28
	s_nop 0
	global_load_lds_dwordx4 v[214:215], off
	s_mov_b32 m0, s3
	s_nop 0
	global_load_lds_dwordx4 v[216:217], off
	s_waitcnt vmcnt(8)
	s_waitcnt lgkmcnt(0)
	s_barrier
; #define PG8_STAGE(bufoff, gbase, voff) do { _Pragma("unroll") for (int _i = 0; _i < 2; ++_i) \
;         __builtin_amdgcn_global_load_lds((const unsigned*)((const char*)(gbase) + (voff)[_i]), (PG8_LAS unsigned*)(lds + (bufoff) + ldsw + _i * 8192), 16, 0, 0); } while (0)
; #define PG8_LDA(dst, b, h) do { _Pragma("unroll") for (int m = 0; m < 4; ++m) _Pragma("unroll") for (int k = 0; k < 2; ++k) dst[m][k] = *(const PG8_LAS bf16x8*)(lds + PG8_SA(b, h) + aoff + m * 2048 + k * 1024); } while (0)
; #define PG8_LDB(dst, b, h) do { _Pragma("unroll") for (int n = 0; n < 2; ++n) _Pragma("unroll") for (int k = 0; k < 2; ++k) dst[n][k] = *(const PG8_LAS bf16x8*)(lds + PG8_SB(b, h) + boff + n * 2048 + k * 1024); } while (0)
; #define PG8_MMA(ai, bj, At, Bt) do { __builtin_amdgcn_s_setprio(1); _Pragma("unroll") for (int m = 0; m < 4; ++m) _Pragma("unroll") for (int n = 0; n < 2; ++n) _Pragma("unroll") for (int k = 0; k < 2; ++k) \
;         acc[ai][bj][m][n] = __builtin_amdgcn_mfma_f32_16x16x32_bf16(Bt[n][k], At[m][k], acc[ai][bj][m][n], 0, 0, 0); __builtin_amdgcn_s_setprio(0); } while (0)
; #define PG8_WAIT_V(n) asm volatile("s_waitcnt vmcnt(" #n ")" ::: "memory")
; #define PG8_WAIT_L(n) asm volatile("s_waitcnt lgkmcnt(" #n ")" ::: "memory")
; #define PG8_BAR __builtin_amdgcn_s_barrier()
; #define PG8_SCHED __builtin_amdgcn_sched_barrier(0)
; template <class Epi, class Sched, bool ALIGN_EPI = false, bool SP2 = false>
; __device__ __forceinline__ void gemm_phase(PG8_LAS unsigned char* lds, const Gemm g, const Sched& S, const Epi& E) {
;     ...
;             PG8_WAIT_V(8); PG8_WAIT_L(0); PG8_BAR; PG8_MMA(1, 0, At, B0); PG8_MMA(1, 1, At, B1); PG8_BAR; PG8_SCHED;
;             PG8_LDB(B0, 1, 0); PG8_LDB(B1, 1, 1); PG8_SCHED; PG8_LDA(At, 1, 0); PG8_STAGE(PG8_SA(0, 1), a2 + hstep, voffA);
;             PG8_WAIT_V(8); PG8_WAIT_L(0); PG8_BAR; PG8_MMA(0, 0, At, B0); PG8_MMA(0, 1, At, B1); PG8_BAR; PG8_SCHED;
	s_setprio 1
	s_waitcnt lgkmcnt(0)
	v_mfma_f32_16x16x32_bf16 v[60:63], v[96:99], v[160:163], v[60:63]
	v_mfma_f32_16x16x32_bf16 v[56:59], v[120:123], v[160:163], v[56:59]
	v_mfma_f32_16x16x32_bf16 v[44:47], v[96:99], v[168:171], v[44:47]
	v_mfma_f32_16x16x32_bf16 v[40:43], v[120:123], v[168:171], v[40:43]
	v_mfma_f32_16x16x32_bf16 v[28:31], v[96:99], v[176:179], v[28:31]
	v_mfma_f32_16x16x32_bf16 v[24:27], v[120:123], v[176:179], v[24:27]
	v_mfma_f32_16x16x32_bf16 v[12:15], v[96:99], v[184:187], v[12:15]
	v_mfma_f32_16x16x32_bf16 v[8:11], v[120:123], v[184:187], v[8:11]
	v_mfma_f32_16x16x32_bf16 v[60:63], v[108:111], v[164:167], v[60:63]
	v_mfma_f32_16x16x32_bf16 v[56:59], v[124:127], v[164:167], v[56:59]
	v_mfma_f32_16x16x32_bf16 v[44:47], v[108:111], v[172:175], v[44:47]
	v_mfma_f32_16x16x32_bf16 v[40:43], v[124:127], v[172:175], v[40:43]
	v_mfma_f32_16x16x32_bf16 v[28:31], v[108:111], v[180:183], v[28:31]
	v_mfma_f32_16x16x32_bf16 v[24:27], v[124:127], v[180:183], v[24:27]
	v_mfma_f32_16x16x32_bf16 v[12:15], v[108:111], v[188:191], v[12:15]
	v_mfma_f32_16x16x32_bf16 v[8:11], v[124:127], v[188:191], v[8:11]
	v_mfma_f32_16x16x32_bf16 v[52:55], v[136:139], v[160:163], v[52:55]
	v_mfma_f32_16x16x32_bf16 v[48:51], v[152:155], v[160:163], v[48:51]
	v_mfma_f32_16x16x32_bf16 v[36:39], v[136:139], v[168:171], v[36:39]
	v_mfma_f32_16x16x32_bf16 v[32:35], v[152:155], v[168:171], v[32:35]
	v_mfma_f32_16x16x32_bf16 v[20:23], v[136:139], v[176:179], v[20:23]
	v_mfma_f32_16x16x32_bf16 v[16:19], v[152:155], v[176:179], v[16:19]
	v_mfma_f32_16x16x32_bf16 v[4:7], v[136:139], v[184:187], v[4:7]
	v_mfma_f32_16x16x32_bf16 v[0:3], v[152:155], v[184:187], v[0:3]
	v_mfma_f32_16x16x32_bf16 v[52:55], v[140:143], v[164:167], v[52:55]
	v_mfma_f32_16x16x32_bf16 v[48:51], v[156:159], v[164:167], v[48:51]
	v_mfma_f32_16x16x32_bf16 v[36:39], v[140:143], v[172:175], v[36:39]
	v_mfma_f32_16x16x32_bf16 v[32:35], v[156:159], v[172:175], v[32:35]
	v_mfma_f32_16x16x32_bf16 v[20:23], v[140:143], v[180:183], v[20:23]
	v_mfma_f32_16x16x32_bf16 v[16:19], v[156:159], v[180:183], v[16:19]
	v_mfma_f32_16x16x32_bf16 v[4:7], v[140:143], v[188:191], v[4:7]
	v_mfma_f32_16x16x32_bf16 v[0:3], v[156:159], v[188:191], v[0:3]
	s_setprio 0
	s_barrier
	s_add_i32 s43, 0, 0x18000
	s_add_i32 s44, 0, 0x1c000
	v_add_u32_e32 v124, s43, v232
	v_add_u32_e32 v156, s44, v232
	ds_read_b128 v[96:99], v124
	ds_read_b128 v[108:111], v124 offset:1024
	ds_read_b128 v[120:123], v124 offset:2048
	ds_read_b128 v[124:127], v124 offset:3072
	ds_read_b128 v[136:139], v156
	ds_read_b128 v[140:143], v156 offset:1024
	ds_read_b128 v[152:155], v156 offset:2048
	ds_read_b128 v[156:159], v156 offset:3072
	s_add_u32 s26, s26, 0x40000
	s_addc_u32 s27, s27, 0
	s_mov_b32 m0, s29
	v_lshl_add_u64 v[220:221], s[26:27], 0, v[208:209]
	ds_read_b128 v[160:163], v243 offset:32768
	ds_read_b128 v[164:167], v243 offset:33792
	ds_read_b128 v[168:171], v243 offset:34816
	ds_read_b128 v[172:175], v243 offset:35840
	ds_read_b128 v[176:179], v243 offset:36864
	ds_read_b128 v[180:183], v243 offset:37888
	ds_read_b128 v[184:187], v243 offset:38912
	ds_read_b128 v[188:191], v243 offset:39936
	global_load_lds_dwordx4 v[220:221], off
	v_lshl_add_u64 v[220:221], s[26:27], 0, v[204:205]
	s_mov_b32 m0, s30
	s_nop 0
	global_load_lds_dwordx4 v[220:221], off
	s_waitcnt vmcnt(8)
	s_waitcnt lgkmcnt(0)
	s_barrier
	s_setprio 1
	s_waitcnt lgkmcnt(0)
	v_mfma_f32_16x16x32_bf16 v[148:151], v[96:99], v[160:163], v[148:151]
	v_mfma_f32_16x16x32_bf16 v[144:147], v[120:123], v[160:163], v[144:147]
	v_mfma_f32_16x16x32_bf16 v[116:119], v[96:99], v[168:171], v[116:119]
	v_mfma_f32_16x16x32_bf16 v[112:115], v[120:123], v[168:171], v[112:115]
	v_mfma_f32_16x16x32_bf16 v[92:95], v[96:99], v[176:179], v[92:95]
	v_mfma_f32_16x16x32_bf16 v[88:91], v[120:123], v[176:179], v[88:91]
	v_mfma_f32_16x16x32_bf16 v[76:79], v[96:99], v[184:187], v[76:79]
	v_mfma_f32_16x16x32_bf16 v[72:75], v[120:123], v[184:187], v[72:75]
	v_mfma_f32_16x16x32_bf16 v[148:151], v[108:111], v[164:167], v[148:151]
	v_mfma_f32_16x16x32_bf16 v[144:147], v[124:127], v[164:167], v[144:147]
	v_mfma_f32_16x16x32_bf16 v[116:119], v[108:111], v[172:175], v[116:119]
	v_mfma_f32_16x16x32_bf16 v[112:115], v[124:127], v[172:175], v[112:115]
	v_mfma_f32_16x16x32_bf16 v[92:95], v[108:111], v[180:183], v[92:95]
	v_mfma_f32_16x16x32_bf16 v[88:91], v[124:127], v[180:183], v[88:91]
	v_mfma_f32_16x16x32_bf16 v[76:79], v[108:111], v[188:191], v[76:79]
	v_mfma_f32_16x16x32_bf16 v[72:75], v[124:127], v[188:191], v[72:75]
	v_mfma_f32_16x16x32_bf16 v[132:135], v[136:139], v[160:163], v[132:135]
	v_mfma_f32_16x16x32_bf16 v[128:131], v[152:155], v[160:163], v[128:131]
	v_mfma_f32_16x16x32_bf16 v[104:107], v[136:139], v[168:171], v[104:107]
	v_mfma_f32_16x16x32_bf16 v[100:103], v[152:155], v[168:171], v[100:103]
	v_mfma_f32_16x16x32_bf16 v[84:87], v[136:139], v[176:179], v[84:87]
	v_mfma_f32_16x16x32_bf16 v[80:83], v[152:155], v[176:179], v[80:83]
	v_mfma_f32_16x16x32_bf16 v[68:71], v[136:139], v[184:187], v[68:71]
	v_mfma_f32_16x16x32_bf16 v[64:67], v[152:155], v[184:187], v[64:67]
	v_mfma_f32_16x16x32_bf16 v[132:135], v[140:143], v[164:167], v[132:135]
	v_mfma_f32_16x16x32_bf16 v[128:131], v[156:159], v[164:167], v[128:131]
	v_mfma_f32_16x16x32_bf16 v[104:107], v[140:143], v[172:175], v[104:107]
	v_mfma_f32_16x16x32_bf16 v[100:103], v[156:159], v[172:175], v[100:103]
	v_mfma_f32_16x16x32_bf16 v[84:87], v[140:143], v[180:183], v[84:87]
	v_mfma_f32_16x16x32_bf16 v[80:83], v[156:159], v[180:183], v[80:83]
	v_mfma_f32_16x16x32_bf16 v[68:71], v[140:143], v[188:191], v[68:71]
	v_mfma_f32_16x16x32_bf16 v[64:67], v[156:159], v[188:191], v[64:67]
	s_setprio 0
	s_barrier
; #define PG8_STAGE(bufoff, gbase, voff) do { _Pragma("unroll") for (int _i = 0; _i < 2; ++_i) \
;         __builtin_amdgcn_global_load_lds((const unsigned*)((const char*)(gbase) + (voff)[_i]), (PG8_LAS unsigned*)(lds + (bufoff) + ldsw + _i * 8192), 16, 0, 0); } while (0)
; #define PG8_LDA(dst, b, h) do { _Pragma("unroll") for (int m = 0; m < 4; ++m) _Pragma("unroll") for (int k = 0; k < 2; ++k) dst[m][k] = *(const PG8_LAS bf16x8*)(lds + PG8_SA(b, h) + aoff + m * 2048 + k * 1024); } while (0)
; #define PG8_MMA(ai, bj, At, Bt) do { __builtin_amdgcn_s_setprio(1); _Pragma("unroll") for (int m = 0; m < 4; ++m) _Pragma("unroll") for (int n = 0; n < 2; ++n) _Pragma("unroll") for (int k = 0; k < 2; ++k) \
;         acc[ai][bj][m][n] = __builtin_amdgcn_mfma_f32_16x16x32_bf16(Bt[n][k], At[m][k], acc[ai][bj][m][n], 0, 0, 0); __builtin_amdgcn_s_setprio(0); } while (0)
; #define PG8_WAIT_V(n) asm volatile("s_waitcnt vmcnt(" #n ")" ::: "memory")
; #define PG8_WAIT_L(n) asm volatile("s_waitcnt lgkmcnt(" #n ")" ::: "memory")
; #define PG8_BAR __builtin_amdgcn_s_barrier()
; #define PG8_SCHED __builtin_amdgcn_sched_barrier(0)
; template <class Epi, class Sched, bool ALIGN_EPI = false, bool SP2 = false>
; __device__ __forceinline__ void gemm_phase(PG8_LAS unsigned char* lds, const Gemm g, const Sched& S, const Epi& E) {
;     ...
;             PG8_LDA(At, 1, 1); PG8_STAGE(PG8_SB(1, 0), b3, voffB); PG8_STAGE(PG8_SB(1, 1), b3 + hstep, voffB); PG8_STAGE(PG8_SA(1, 0), a3, voffA);
;             PG8_WAIT_V(8); PG8_WAIT_L(0); PG8_BAR; PG8_MMA(1, 0, At, B0); PG8_MMA(1, 1, At, B1); PG8_BAR; PG8_SCHED;
;     ...
;         if constexpr (ALIGN_EPI) { if (wr == 0) PG8_BAR; }
	s_add_i32 s26, s43, s2
	v_lshl_add_u64 v[196:197], v[196:197], 0, s[0:1]
	s_mov_b32 m0, s26
	ds_read_b128 v[160:163], v243 offset:49152
	ds_read_b128 v[164:167], v243 offset:50176
	ds_read_b128 v[168:171], v243 offset:51200
	ds_read_b128 v[172:175], v243 offset:52224
	ds_read_b128 v[176:179], v243 offset:53248
	ds_read_b128 v[180:183], v243 offset:54272
	ds_read_b128 v[184:187], v243 offset:55296
	ds_read_b128 v[188:191], v243 offset:56320
	global_load_lds_dwordx4 v[196:197], off
	s_add_i32 m0, s26, 0x2000
	s_add_u32 s24, s24, 0x40080
	v_lshl_add_u64 v[196:197], v[198:199], 0, s[0:1]
	s_addc_u32 s25, s25, 0
	s_add_i32 s26, s44, s2
	global_load_lds_dwordx4 v[196:197], off
	v_lshl_add_u64 v[196:197], s[24:25], 0, v[206:207]
	s_mov_b32 m0, s26
	s_nop 0
	global_load_lds_dwordx4 v[196:197], off
	v_lshl_add_u64 v[196:197], s[24:25], 0, v[202:203]
	s_add_i32 m0, s26, 0x2000
	s_nop 0
	global_load_lds_dwordx4 v[196:197], off
	v_lshl_add_u64 v[196:197], v[214:215], 0, s[0:1]
	s_mov_b32 m0, s31
	s_nop 0
	global_load_lds_dwordx4 v[196:197], off
	v_lshl_add_u64 v[196:197], v[216:217], 0, s[0:1]
	s_mov_b32 m0, s34
	s_nop 0
	global_load_lds_dwordx4 v[196:197], off
	s_waitcnt vmcnt(8)
	s_waitcnt lgkmcnt(0)
	s_barrier
	s_setprio 1
	s_waitcnt lgkmcnt(0)
	v_mfma_f32_16x16x32_bf16 v[60:63], v[96:99], v[160:163], v[60:63]
	v_mfma_f32_16x16x32_bf16 v[56:59], v[120:123], v[160:163], v[56:59]
	v_mfma_f32_16x16x32_bf16 v[44:47], v[96:99], v[168:171], v[44:47]
	v_mfma_f32_16x16x32_bf16 v[40:43], v[120:123], v[168:171], v[40:43]
	v_mfma_f32_16x16x32_bf16 v[28:31], v[96:99], v[176:179], v[28:31]
	v_mfma_f32_16x16x32_bf16 v[24:27], v[120:123], v[176:179], v[24:27]
	v_mfma_f32_16x16x32_bf16 v[12:15], v[96:99], v[184:187], v[12:15]
	v_mfma_f32_16x16x32_bf16 v[8:11], v[120:123], v[184:187], v[8:11]
	v_mfma_f32_16x16x32_bf16 v[60:63], v[108:111], v[164:167], v[60:63]
	v_mfma_f32_16x16x32_bf16 v[56:59], v[124:127], v[164:167], v[56:59]
	v_mfma_f32_16x16x32_bf16 v[44:47], v[108:111], v[172:175], v[44:47]
	v_mfma_f32_16x16x32_bf16 v[40:43], v[124:127], v[172:175], v[40:43]
	v_mfma_f32_16x16x32_bf16 v[28:31], v[108:111], v[180:183], v[28:31]
	v_mfma_f32_16x16x32_bf16 v[24:27], v[124:127], v[180:183], v[24:27]
	v_mfma_f32_16x16x32_bf16 v[12:15], v[108:111], v[188:191], v[12:15]
	v_mfma_f32_16x16x32_bf16 v[8:11], v[124:127], v[188:191], v[8:11]
	v_mfma_f32_16x16x32_bf16 v[52:55], v[136:139], v[160:163], v[52:55]
	v_mfma_f32_16x16x32_bf16 v[48:51], v[152:155], v[160:163], v[48:51]
	v_mfma_f32_16x16x32_bf16 v[36:39], v[136:139], v[168:171], v[36:39]
	v_mfma_f32_16x16x32_bf16 v[32:35], v[152:155], v[168:171], v[32:35]
	v_mfma_f32_16x16x32_bf16 v[20:23], v[136:139], v[176:179], v[20:23]
	v_mfma_f32_16x16x32_bf16 v[16:19], v[152:155], v[176:179], v[16:19]
	v_mfma_f32_16x16x32_bf16 v[4:7], v[136:139], v[184:187], v[4:7]
	v_mfma_f32_16x16x32_bf16 v[0:3], v[152:155], v[184:187], v[0:3]
	v_mfma_f32_16x16x32_bf16 v[52:55], v[140:143], v[164:167], v[52:55]
	v_mfma_f32_16x16x32_bf16 v[48:51], v[156:159], v[164:167], v[48:51]
	v_mfma_f32_16x16x32_bf16 v[36:39], v[140:143], v[172:175], v[36:39]
	v_mfma_f32_16x16x32_bf16 v[32:35], v[156:159], v[172:175], v[32:35]
	v_mfma_f32_16x16x32_bf16 v[20:23], v[140:143], v[180:183], v[20:23]
	v_mfma_f32_16x16x32_bf16 v[16:19], v[156:159], v[180:183], v[16:19]
	v_mfma_f32_16x16x32_bf16 v[4:7], v[140:143], v[188:191], v[4:7]
	v_mfma_f32_16x16x32_bf16 v[0:3], v[156:159], v[188:191], v[0:3]
	s_setprio 0
	s_barrier
	s_add_i32 s42, s42, 2
	s_add_u32 s22, s22, 0x100
	s_addc_u32 s23, s23, 0
	s_add_u32 s40, s40, 0x100
	s_addc_u32 s41, s41, 0
	s_cmp_gt_u32 s42, 13
	s_cbranch_scc0 .LBB0_1209
	s_and_b64 vcc, exec, s[12:13]
	s_cbranch_vccz .LBB0_1212
	s_barrier
